# layer-1 weight conversion moved from the prologue to a one-shot pass at the start of phase 7 (between w_gu and w_down of layer 0) + GEMM loop-tail SALU moved into last MFMA block
# baseline (speedup 1.0000x reference)
_Z10hybrid_fwd4Args:
	s_mov_b32 s100, 0
	s_mov_b32 s101, 0x81ff
	v_writelane_b32 v254, s0, 0
	s_nop 1
	v_writelane_b32 v254, s1, 1
	s_load_dwordx2 s[0:1], s[0:1], 0x68
	s_waitcnt lgkmcnt(0)
	v_writelane_b32 v254, s0, 2
	s_nop 1
	v_writelane_b32 v254, s1, 3
	s_cmp_ge_i32 s0, s1
	s_cbranch_scc1 .LBB0_675
	v_readlane_b32 s0, v254, 0
	v_readlane_b32 s1, v254, 1
	s_load_dwordx2 s[34:35], s[0:1], 0x60
	s_add_u32 s0, s0, 0x70
	s_addc_u32 s1, s1, 0
	v_writelane_b32 v254, s0, 4
	s_cmpk_lt_i32 s2, 0x200
	s_mov_b32 s75, s2
	v_writelane_b32 v254, s1, 5
	s_cselect_b64 s[0:1], -1, 0
	v_writelane_b32 v254, s0, 6
	v_and_b32_e32 v238, 0x3ff, v0
	v_and_b32_e32 v0, 0x3fffffff, v0
	v_writelane_b32 v254, s1, 7
	s_ashr_i32 s0, s2, 31
	s_lshr_b32 s0, s0, 29
	s_add_i32 s0, s2, s0
	s_ashr_i32 s1, s0, 3
	s_and_b32 s0, s0, -8
	s_sub_i32 s3, s2, s0
	s_lshl_b32 s0, s3, 6
	s_cmpk_lt_i32 s2, 0xc00
	s_cselect_b64 s[4:5], -1, 0
	v_writelane_b32 v254, s4, 8
	s_cmpk_lt_i32 s2, 0xb00
	s_mov_b32 s93, 0
	v_writelane_b32 v254, s5, 9
	s_cselect_b64 s[4:5], -1, 0
	v_writelane_b32 v254, s4, 10
	s_lshl_b32 s2, s2, 3
	s_movk_i32 s78, 0x2000
	v_writelane_b32 v254, s5, 11
	v_writelane_b32 v254, s2, 12
	s_lshl_b32 s2, s75, 9
	v_writelane_b32 v254, s2, 13
	s_and_b32 s2, s75, 7
	s_xor_b32 s4, s2, 7
	s_lshl_b32 s2, s2, 8
	v_writelane_b32 v254, s4, 14
	s_waitcnt lgkmcnt(0)
	s_add_u32 s4, s34, s2
	s_addc_u32 s5, s35, 0
	v_writelane_b32 v254, s4, 15
	s_cmp_lt_i32 s3, 0
	s_mul_i32 s2, s3, 0x41
	v_writelane_b32 v254, s5, 16
	v_cmp_eq_u32_e64 s[4:5], 0, v238
	s_cselect_b32 s0, s2, s0
	s_movk_i32 s2, 0x181
	v_writelane_b32 v254, s4, 17
	s_cselect_b32 s2, s2, 0x180
	s_mul_i32 s2, s3, s2
	v_writelane_b32 v254, s5, 18
	v_cmp_eq_u32_e64 s[4:5], 0, v0
	v_mbcnt_lo_u32_b32 v0, -1, 0
	v_mov_b32_e32 v65, 0
	v_writelane_b32 v254, s4, 19
	s_mov_b64 s[98:99], 0x80
	s_movk_i32 s33, 0x3000
	v_writelane_b32 v254, s5, 20
	s_movk_i32 s4, 0x161
	s_cselect_b32 s4, s4, 0x160
	s_add_i32 s0, s0, s1
	s_ashr_i32 s5, s0, 31
	s_lshr_b32 s5, s5, 26
	s_add_i32 s5, s0, s5
	s_ashr_i32 s6, s5, 6
	s_and_b32 s5, s5, 0xffc0
	s_sub_i32 s5, s0, s5
	s_bfe_i32 s0, s5, 0x80000
	s_bfe_u32 s0, s0, 0x3000c
	s_add_i32 s7, s5, s0
	s_bfe_i32 s0, s7, 0x80000
	s_and_b32 s7, s7, 0xf8
	s_sub_i32 s5, s5, s7
	s_lshl_b32 s6, s6, 3
	s_sext_i32_i8 s5, s5
	s_sext_i32_i16 s8, s0
	s_add_i32 s5, s6, s5
	v_writelane_b32 v254, s5, 21
	s_ashr_i32 s5, s8, 3
	s_add_i32 s2, s2, s1
	v_writelane_b32 v254, s5, 22
	s_mul_hi_i32 s5, s2, 0x2aaaaaab
	s_lshr_b32 s6, s5, 31
	s_ashr_i32 s5, s5, 6
	s_add_i32 s5, s5, s6
	s_mul_i32 s6, s5, 0x180
	s_sub_i32 s6, s2, s6
	s_bfe_u32 s2, s6, 0x3001c
	s_add_i32 s7, s6, s2
	s_mul_i32 s3, s3, s4
	s_lshr_b32 s0, s8, 3
	s_sext_i32_i16 s8, s7
	s_and_b32 s7, s7, 0xfff8
	s_add_i32 s3, s3, s1
	s_sub_i32 s6, s6, s7
	s_mul_hi_i32 s1, s3, 0x2e8ba2e9
	s_lshl_b32 s5, s5, 3
	s_sext_i32_i16 s6, s6
	s_lshr_b32 s4, s1, 31
	s_ashr_i32 s1, s1, 6
	s_add_i32 s10, s5, s6
	s_ashr_i32 s5, s8, 3
	s_add_i32 s1, s1, s4
	v_writelane_b32 v254, s5, 23
	s_lshl_b32 s5, s1, 3
	s_mulk_i32 s1, 0x160
	s_sub_i32 s1, s3, s1
	s_bfe_u32 s3, s1, 0x3001c
	s_add_i32 s3, s1, s3
	s_sext_i32_i16 s6, s3
	s_and_b32 s3, s3, 0xfff8
	s_sub_i32 s1, s1, s3
	s_sext_i32_i16 s1, s1
	s_lshr_b32 s2, s8, 3
	s_add_i32 s8, s5, s1
	s_ashr_i32 s1, s6, 3
	s_lshr_b32 s4, s6, 3
	v_writelane_b32 v254, s1, 24
	s_mov_b32 s6, s8
	s_ashr_i32 s9, s8, 31
	v_writelane_b32 v254, s6, 25
	s_bfe_i64 s[4:5], s[4:5], 0x100000
	s_lshl_b64 s[4:5], s[4:5], 20
	v_writelane_b32 v254, s7, 26
	s_lshl_b64 s[6:7], s[8:9], 20
	v_writelane_b32 v254, s6, 27
	s_ashr_i32 s11, s10, 31
	v_mov_b32_e32 v239, 0x22c00
	v_writelane_b32 v254, s7, 28
	v_writelane_b32 v254, s4, 29
	s_mov_b32 s89, 0xbfb8aa3b
	s_mov_b32 s82, 0x800000
	v_writelane_b32 v254, s5, 30
	s_bfe_i64 s[4:5], s[0:1], 0x100000
	s_mov_b32 s0, s4
	v_writelane_b32 v254, s0, 31
	s_mov_b32 s83, 0x3f317217
	v_mov_b32_e32 v231, 0x260
	v_writelane_b32 v254, s1, 32
	s_lshl_b64 s[0:1], s[4:5], 20
	v_writelane_b32 v254, s0, 33
	s_mov_b32 s4, 0x3e0293ee
	s_mov_b64 s[96:97], 0x60000
	v_writelane_b32 v254, s1, 34
	s_mov_b32 s0, s10
	v_writelane_b32 v254, s0, 35
	v_mov_b32_e32 v230, 0x358637bd
	v_mov_b32_e32 v232, 0xfff
	v_writelane_b32 v254, s1, 36
	s_lshl_b64 s[0:1], s[10:11], 20
	v_writelane_b32 v254, s0, 37
	v_mbcnt_hi_u32_b32 v233, -1, v0
	v_mov_b32_e32 v234, 0x41b17218
	v_writelane_b32 v254, s1, 38
	s_bfe_i64 s[0:1], s[2:3], 0x100000
	s_lshl_b64 s[0:1], s[0:1], 20
	v_writelane_b32 v254, s0, 39
	s_mov_b32 s3, 0x7f800000
	v_mov_b32_e32 v235, 0xf149f2ca
	v_writelane_b32 v254, s1, 40
	v_mov_b32_e32 v236, 0x3000
	v_readlane_b32 s0, v254, 2
	v_readlane_b32 s1, v254, 3
	v_writelane_b32 v254, s75, 41
	v_writelane_b32 v254, s34, 42
	v_mov_b32_e32 v237, 0x10000
	s_mov_b32 s2, 0
	s_mov_b32 s5, s0
	v_writelane_b32 v254, s35, 43
	s_branch .LBB0_4
.Lpp_done:
	s_waitcnt vmcnt(0) lgkmcnt(0)
	s_barrier
	s_mov_b32 s101, 0x81ff
	s_mov_b32 s5, s91
	v_readlane_b32 s2, v254, 44

.LBB0_4:
	v_writelane_b32 v254, s2, 44
	v_mov_b32_e32 v194, v238
	v_readlane_b32 s0, v254, 0
	v_readlane_b32 s1, v254, 1
	s_load_dwordx2 s[94:95], s[0:1], 0x60
	s_load_dwordx16 s[56:71], s[0:1], 0x0
	s_load_dwordx8 s[8:15], s[0:1], 0x40
	v_readfirstlane_b32 s2, v194
	s_ashr_i32 s86, s2, 6
	v_and_b32_e32 v240, 63, v194
	s_mov_b32 s91, s5
	s_waitcnt lgkmcnt(0)
	v_writelane_b32 v254, s8, 45
	s_nop 1
	v_writelane_b32 v254, s9, 46
	v_writelane_b32 v254, s10, 47
	v_writelane_b32 v254, s11, 48
	v_writelane_b32 v254, s12, 49
	v_writelane_b32 v254, s13, 50
	v_writelane_b32 v254, s14, 51
	v_writelane_b32 v254, s15, 52
	s_nop 0
	v_readlane_b32 s0, v254, 4
	v_readlane_b32 s1, v254, 5
	s_load_dword s0, s[0:1], 0x0
	s_waitcnt lgkmcnt(0)
	v_writelane_b32 v254, s0, 53
	s_add_u32 s0, s94, 0x10000
	s_addc_u32 s1, s95, 0
	v_writelane_b32 v254, s0, 54
	s_nop 0
	s_nop 0
	v_writelane_b32 v254, s1, 55
	s_cmp_lg_u32 s5, 7
	s_cbranch_scc1 .Lpp_no
	s_cmp_lg_u32 s100, 0
	s_cbranch_scc1 .Lpp_no
	s_mov_b32 s100, 1
	s_mov_b32 s101, 0x103ff
	s_mov_b64 s[0:1], -1
	s_branch .LBB0_465
.Lpp_no:
	s_cmp_lg_u32 s5, 0
	s_mov_b64 s[0:1], -1
	s_cbranch_scc0 .LBB0_465
	s_add_i32 s0, s91, -1
	s_mul_hi_i32 s1, s0, 0x92492493
	s_add_i32 s1, s1, s0
	s_lshr_b32 s5, s1, 31
	s_ashr_i32 s1, s1, 2
	s_add_i32 s8, s1, s5
	s_mul_i32 s1, s8, 7
	s_sub_i32 s5, s0, s1
	s_add_u32 s80, s94, 0x10800000
	s_addc_u32 s81, s95, 0
	s_add_u32 s84, s94, 0x14800000
	s_addc_u32 s85, s95, 0
	s_add_u32 s18, s94, 0x20800000
	s_mov_b32 s6, s8
	s_addc_u32 s19, s95, 0
	v_writelane_b32 v254, s6, 56
	s_add_u32 s0, s94, 0x14801000
	s_addc_u32 s1, s95, 0
	v_writelane_b32 v254, s7, 57
	v_writelane_b32 v254, s0, 58
	s_mov_b64 s[6:7], -1
	s_cmp_lt_i32 s5, 2
	v_writelane_b32 v254, s1, 59
	v_writelane_b32 v254, s5, 60
	s_mov_b64 s[0:1], 0
	v_writelane_b32 v254, s0, 61
	s_nop 1
	v_writelane_b32 v254, s1, 62
	v_writelane_b32 v254, s91, 63
	s_cbranch_scc1 .LBB0_151
	v_readlane_b32 s0, v254, 60
	s_cmp_gt_i32 s0, 2
	s_cbranch_scc0 .LBB0_37
	s_cmp_eq_u32 s0, 3
	s_mov_b64 s[0:1], -1
	s_cbranch_scc0 .LBB0_40
	v_readlane_b32 s0, v254, 6
	v_readlane_b32 s1, v254, 7
	s_andn2_b64 vcc, exec, s[0:1]
	v_readfirstlane_b32 s6, v194
	s_cbranch_vccnz .LBB0_39
	v_lshlrev_b32_e32 v3, 4, v194
	v_add_u32_e32 v0, 0x2000, v3
	v_ashrrev_i32_e32 v1, 31, v0
	v_lshrrev_b32_e32 v1, 22, v1
	v_add_u32_e32 v1, v0, v1
	v_ashrrev_i32_e32 v1, 10, v1
	v_mul_i32_i24_e32 v2, 0x400, v1
	v_sub_u32_e32 v0, v0, v2
	v_lshrrev_b32_e32 v2, 4, v0
	v_readlane_b32 s0, v254, 56
	v_bitop3_b32 v2, v2, v0, 32 bitop3:0x6c
	v_readlane_b32 s1, v254, 57
	v_ashrrev_i32_e32 v0, 31, v2
	s_mov_b32 s8, s0
	s_ashr_i32 s9, s0, 31
	v_writelane_b32 v254, s0, 56
	v_lshrrev_b32_e32 v0, 26, v0
	v_add_u32_e32 v4, v2, v0
	v_writelane_b32 v254, s1, 57
	v_lshlrev_b32_e32 v5, 3, v1
	s_lshl_b64 s[0:1], s[8:9], 23
	v_readlane_b32 s8, v254, 45
	v_ashrrev_i32_e32 v0, 6, v4
	v_and_b32_e32 v5, -16, v5
	v_readlane_b32 s9, v254, 46
	v_add_u32_e32 v5, v0, v5
	v_and_b32_e32 v0, 3, v0
	s_mov_b32 s9, 0xfffe0
	v_lshrrev_b32_e32 v6, 2, v5
	v_lshlrev_b32_e32 v7, 1, v5
	v_and_or_b32 v0, v5, s9, v0
	v_and_b32_e32 v6, 4, v6
	v_and_b32_e32 v7, 24, v7
	s_add_u32 s0, s94, s0
	v_or3_b32 v6, v0, v6, v7
	v_lshlrev_b32_e32 v0, 5, v1
	v_and_b32_e32 v1, 0xc0, v4
	s_addc_u32 s1, s95, s1
	v_sub_u32_e32 v1, v2, v1
	v_mov_b32_e32 v10, 1
	s_add_u32 s0, s0, 0x6400000
	v_ashrrev_i16_sdwa v1, v10, sext(v1) dst_sel:DWORD dst_unused:UNUSED_PAD src0_sel:DWORD src1_sel:BYTE_0
	s_addc_u32 s1, s1, 0
	s_add_i32 s5, s91, 5
	v_and_b32_e32 v0, 32, v0
	v_bfe_i32 v1, v1, 0, 16
	s_cmp_lt_u32 s5, 13
	s_movk_i32 s7, 0x800
	v_add_u32_e32 v4, v0, v1
	s_cselect_b32 s8, s7, 0x1800
	v_lshlrev_b32_e32 v2, 1, v4
	v_lshl_add_u32 v164, v6, 12, v2
	v_mul_lo_u32 v2, v5, s8
	v_add_lshl_u32 v166, v4, v2, 1
	v_bfe_i32 v4, v194, 27, 1
	v_lshrrev_b32_e32 v4, 22, v4
	v_add_u32_e32 v4, v3, v4
	v_and_b32_e32 v4, 0xfffffc00, v4
	v_sub_u32_e32 v3, v3, v4
	v_lshrrev_b32_e32 v4, 4, v3
	v_ashrrev_i32_e32 v6, 31, v194
	v_bitop3_b32 v4, v4, v3, 32 bitop3:0x6c
	v_lshrrev_b32_e32 v6, 26, v6
	v_ashrrev_i32_e32 v3, 31, v4
	v_add_u32_e32 v6, v194, v6
	v_lshrrev_b32_e32 v3, 26, v3
	v_ashrrev_i32_e32 v6, 6, v6
	v_add_u32_e32 v5, v4, v3
	v_lshlrev_b32_e32 v7, 3, v6
	v_ashrrev_i32_e32 v3, 6, v5
	v_and_b32_e32 v7, -16, v7
	v_add_u32_e32 v7, v3, v7
	v_and_b32_e32 v3, 3, v3
	v_lshrrev_b32_e32 v8, 2, v7
	v_lshlrev_b32_e32 v9, 1, v7
	v_and_b32_e32 v5, 0xc0, v5
	v_and_or_b32 v3, v7, s9, v3
	v_and_b32_e32 v8, 4, v8
	v_and_b32_e32 v9, 24, v9
	v_sub_u32_e32 v4, v4, v5
	v_or3_b32 v8, v3, v8, v9
	v_lshlrev_b32_e32 v3, 5, v6
	v_ashrrev_i16_sdwa v4, v10, sext(v4) dst_sel:DWORD dst_unused:UNUSED_PAD src0_sel:DWORD src1_sel:BYTE_0
	v_and_b32_e32 v3, 32, v3
	v_bfe_i32 v4, v4, 0, 16
	v_add_u32_e32 v6, v3, v4
	v_readlane_b32 s10, v254, 47
	v_readlane_b32 s14, v254, 51
	v_readlane_b32 s15, v254, 52
	v_lshlrev_b32_e32 v5, 1, v6
	v_readlane_b32 s11, v254, 48
	v_readlane_b32 s12, v254, 49
	s_cselect_b32 s5, s15, s85
	s_cselect_b32 s14, s14, s84
	s_ashr_i32 s10, s6, 6
	s_lshl_b32 s92, s8, 8
	s_lshl_b32 s15, s8, 9
	v_lshl_add_u32 v168, v8, 12, v5
	v_mul_lo_u32 v5, v7, s8
	v_readlane_b32 s8, v254, 21
	s_ashr_i32 s7, s6, 8
	s_lshl_b32 s30, s10, 10
	s_mul_hi_i32 s11, s15, s8
	s_mul_i32 s12, s15, s8
	v_readlane_b32 s8, v254, 33
	v_readlane_b32 s9, v254, 34
	s_add_u32 s26, s0, s8
	s_addc_u32 s27, s1, s9
	s_add_i32 s31, s30, 0x10000
	s_add_i32 s34, s30, 0x12000
	s_mov_b32 m0, s31
	s_add_u32 s8, s26, 0x80000
	global_load_lds_dwordx4 v168, s[26:27]
	s_mov_b32 m0, s34
	s_addc_u32 s9, s27, 0
	s_add_i32 s35, s30, 0x14000
	s_add_i32 s36, s30, 0x16000
	global_load_lds_dwordx4 v164, s[26:27]
	s_mov_b32 m0, s35
	s_add_u32 s22, s14, s12
	global_load_lds_dwordx4 v168, s[8:9]
	s_mov_b32 m0, s36
	s_addc_u32 s23, s5, s11
	s_add_i32 s37, s30, 0x2000
	v_add_lshl_u32 v170, v6, v5, 1
	global_load_lds_dwordx4 v164, s[8:9]
	s_mov_b32 m0, s30
	s_add_u32 s8, s22, s92
	global_load_lds_dwordx4 v170, s[22:23]
	s_mov_b32 m0, s37
	s_addc_u32 s9, s23, 0
	s_add_i32 s38, s30, 0x4000
	global_load_lds_dwordx4 v166, s[22:23]
	s_mov_b32 m0, s38
	s_add_i32 s39, s30, 0x6000
	global_load_lds_dwordx4 v170, s[8:9]
	s_mov_b32 m0, s39
	s_cmp_eq_u32 s7, 1
	global_load_lds_dwordx4 v166, s[8:9]
	s_cselect_b64 s[8:9], -1, 0
	s_cmp_lg_u32 s7, 1
	v_readlane_b32 s13, v254, 50
	s_cbranch_scc1 .LBB0_11
	s_barrier

.LBB0_25:
	ds_read_b128 v[132:135], v181
	ds_read_b128 v[136:139], v182
	ds_read_b128 v[140:143], v183
	ds_read_b128 v[144:147], v184
	ds_read_b128 v[148:151], v185
	ds_read_b128 v[152:155], v186
	ds_read_b128 v[156:159], v187
	ds_read_b128 v[160:163], v188
	s_add_i32 s73, s28, 2
	s_add_u32 s26, s22, 0x80
	s_addc_u32 s27, s23, 0
	s_cmp_eq_u32 s54, s28
	s_cselect_b32 s28, s16, s26
	s_cselect_b32 s29, s17, s27
	s_cselect_b32 s27, s21, s72
	s_cselect_b32 s26, s20, s55
	s_mov_b32 m0, s46
	ds_read_b128 v[198:201], v179
	ds_read_b128 v[202:205], v179 offset:1024
	ds_read_b128 v[206:209], v179 offset:2048
	ds_read_b128 v[210:213], v179 offset:3072
	ds_read_b128 v[214:217], v179 offset:4096
	ds_read_b128 v[218:221], v179 offset:5120
	ds_read_b128 v[222:225], v179 offset:6144
	ds_read_b128 v[242:245], v179 offset:7168
	global_load_lds_dwordx4 v172, s[22:23]
	s_mov_b32 m0, s47
	s_nop 0
	global_load_lds_dwordx4 v174, s[22:23]
	s_waitcnt vmcnt(8)
	s_waitcnt lgkmcnt(0)
	s_barrier
	s_setprio 1
	v_mfma_f32_16x16x32_bf16 v[128:131], v[132:135], v[198:201], v[128:131]
	v_mfma_f32_16x16x32_bf16 v[124:127], v[140:143], v[198:201], v[124:127]
	v_mfma_f32_16x16x32_bf16 v[120:123], v[132:135], v[206:209], v[120:123]
	v_mfma_f32_16x16x32_bf16 v[116:119], v[140:143], v[206:209], v[116:119]
	v_mfma_f32_16x16x32_bf16 v[112:115], v[132:135], v[214:217], v[112:115]
	v_mfma_f32_16x16x32_bf16 v[108:111], v[140:143], v[214:217], v[108:111]
	v_mfma_f32_16x16x32_bf16 v[104:107], v[132:135], v[222:225], v[104:107]
	v_mfma_f32_16x16x32_bf16 v[100:103], v[140:143], v[222:225], v[100:103]
	v_mfma_f32_16x16x32_bf16 v[128:131], v[136:139], v[202:205], v[128:131]
	v_mfma_f32_16x16x32_bf16 v[124:127], v[144:147], v[202:205], v[124:127]
	v_mfma_f32_16x16x32_bf16 v[120:123], v[136:139], v[210:213], v[120:123]
	v_mfma_f32_16x16x32_bf16 v[116:119], v[144:147], v[210:213], v[116:119]
	v_mfma_f32_16x16x32_bf16 v[112:115], v[136:139], v[218:221], v[112:115]
	v_mfma_f32_16x16x32_bf16 v[108:111], v[144:147], v[218:221], v[108:111]
	v_mfma_f32_16x16x32_bf16 v[104:107], v[136:139], v[242:245], v[104:107]
	v_mfma_f32_16x16x32_bf16 v[100:103], v[144:147], v[242:245], v[100:103]
	s_setprio 0
	s_setprio 1
	v_mfma_f32_16x16x32_bf16 v[96:99], v[148:151], v[198:201], v[96:99]
	v_mfma_f32_16x16x32_bf16 v[92:95], v[156:159], v[198:201], v[92:95]
	v_mfma_f32_16x16x32_bf16 v[88:91], v[148:151], v[206:209], v[88:91]
	v_mfma_f32_16x16x32_bf16 v[84:87], v[156:159], v[206:209], v[84:87]
	v_mfma_f32_16x16x32_bf16 v[80:83], v[148:151], v[214:217], v[80:83]
	v_mfma_f32_16x16x32_bf16 v[76:79], v[156:159], v[214:217], v[76:79]
	v_mfma_f32_16x16x32_bf16 v[72:75], v[148:151], v[222:225], v[72:75]
	v_mfma_f32_16x16x32_bf16 v[66:69], v[156:159], v[222:225], v[68:71]
	v_mfma_f32_16x16x32_bf16 v[96:99], v[152:155], v[202:205], v[96:99]
	v_mfma_f32_16x16x32_bf16 v[92:95], v[160:163], v[202:205], v[92:95]
	v_mfma_f32_16x16x32_bf16 v[88:91], v[152:155], v[210:213], v[88:91]
	v_mfma_f32_16x16x32_bf16 v[84:87], v[160:163], v[210:213], v[84:87]
	v_mfma_f32_16x16x32_bf16 v[80:83], v[152:155], v[218:221], v[80:83]
	v_mfma_f32_16x16x32_bf16 v[76:79], v[160:163], v[218:221], v[76:79]
	v_mfma_f32_16x16x32_bf16 v[72:75], v[152:155], v[242:245], v[72:75]
	v_mfma_f32_16x16x32_bf16 v[66:69], v[160:163], v[242:245], v[66:69]
	s_setprio 0
	s_barrier
	s_mov_b32 m0, s31
	s_add_u32 s74, s26, 0x80000
	s_addc_u32 s75, s27, 0
	ds_read_b128 v[198:201], v179 offset:16384
	ds_read_b128 v[202:205], v179 offset:17408
	ds_read_b128 v[206:209], v179 offset:18432
	ds_read_b128 v[210:213], v179 offset:19456
	ds_read_b128 v[214:217], v179 offset:20480
	ds_read_b128 v[218:221], v179 offset:21504
	ds_read_b128 v[222:225], v179 offset:22528
	ds_read_b128 v[242:245], v179 offset:23552
	global_load_lds_dwordx4 v168, s[26:27]
	s_mov_b32 m0, s34
	s_nop 0
	global_load_lds_dwordx4 v164, s[26:27]
	s_mov_b32 m0, s35
	s_nop 0
	global_load_lds_dwordx4 v168, s[74:75]
	s_mov_b32 m0, s36
	s_nop 0
	global_load_lds_dwordx4 v164, s[74:75]
	s_mov_b32 m0, s30
	s_nop 0
	global_load_lds_dwordx4 v170, s[28:29]
	s_mov_b32 m0, s37
	s_nop 0
	global_load_lds_dwordx4 v166, s[28:29]
	s_waitcnt vmcnt(8)
	s_waitcnt lgkmcnt(0)
	s_barrier
	s_setprio 1
	v_mfma_f32_16x16x32_bf16 v[60:63], v[132:135], v[198:201], v[60:63]
	v_mfma_f32_16x16x32_bf16 v[56:59], v[140:143], v[198:201], v[56:59]
	v_mfma_f32_16x16x32_bf16 v[52:55], v[132:135], v[206:209], v[52:55]
	v_mfma_f32_16x16x32_bf16 v[48:51], v[140:143], v[206:209], v[48:51]
	v_mfma_f32_16x16x32_bf16 v[44:47], v[132:135], v[214:217], v[44:47]
	v_mfma_f32_16x16x32_bf16 v[40:43], v[140:143], v[214:217], v[40:43]
	v_mfma_f32_16x16x32_bf16 v[36:39], v[132:135], v[222:225], v[36:39]
	v_mfma_f32_16x16x32_bf16 v[32:35], v[140:143], v[222:225], v[32:35]
	v_mfma_f32_16x16x32_bf16 v[60:63], v[136:139], v[202:205], v[60:63]
	v_mfma_f32_16x16x32_bf16 v[56:59], v[144:147], v[202:205], v[56:59]
	v_mfma_f32_16x16x32_bf16 v[52:55], v[136:139], v[210:213], v[52:55]
	v_mfma_f32_16x16x32_bf16 v[48:51], v[144:147], v[210:213], v[48:51]
	v_mfma_f32_16x16x32_bf16 v[44:47], v[136:139], v[218:221], v[44:47]
	v_mfma_f32_16x16x32_bf16 v[40:43], v[144:147], v[218:221], v[40:43]
	v_mfma_f32_16x16x32_bf16 v[36:39], v[136:139], v[242:245], v[36:39]
	v_mfma_f32_16x16x32_bf16 v[32:35], v[144:147], v[242:245], v[32:35]
	s_setprio 0
	s_setprio 1
	v_mfma_f32_16x16x32_bf16 v[28:31], v[148:151], v[198:201], v[28:31]
	v_mfma_f32_16x16x32_bf16 v[24:27], v[156:159], v[198:201], v[24:27]
	v_mfma_f32_16x16x32_bf16 v[20:23], v[148:151], v[206:209], v[20:23]
	v_mfma_f32_16x16x32_bf16 v[16:19], v[156:159], v[206:209], v[16:19]
	v_mfma_f32_16x16x32_bf16 v[12:15], v[148:151], v[214:217], v[12:15]
	v_mfma_f32_16x16x32_bf16 v[8:11], v[156:159], v[214:217], v[8:11]
	v_mfma_f32_16x16x32_bf16 v[4:7], v[148:151], v[222:225], v[4:7]
	v_mfma_f32_16x16x32_bf16 v[0:3], v[156:159], v[222:225], v[0:3]
	v_mfma_f32_16x16x32_bf16 v[28:31], v[152:155], v[202:205], v[28:31]
	v_mfma_f32_16x16x32_bf16 v[24:27], v[160:163], v[202:205], v[24:27]
	v_mfma_f32_16x16x32_bf16 v[20:23], v[152:155], v[210:213], v[20:23]
	v_mfma_f32_16x16x32_bf16 v[16:19], v[160:163], v[210:213], v[16:19]
	v_mfma_f32_16x16x32_bf16 v[12:15], v[152:155], v[218:221], v[12:15]
	v_mfma_f32_16x16x32_bf16 v[8:11], v[160:163], v[218:221], v[8:11]
	v_mfma_f32_16x16x32_bf16 v[4:7], v[152:155], v[242:245], v[4:7]
	v_mfma_f32_16x16x32_bf16 v[0:3], v[160:163], v[242:245], v[0:3]
	s_setprio 0
	s_barrier
	ds_read_b128 v[132:135], v189
	ds_read_b128 v[136:139], v190
	ds_read_b128 v[140:143], v191
	ds_read_b128 v[144:147], v192
	ds_read_b128 v[148:151], v193
	ds_read_b128 v[152:155], v195
	ds_read_b128 v[156:159], v196
	ds_read_b128 v[160:163], v197
	s_add_u32 s56, s28, s92
	s_addc_u32 s57, s29, 0
	s_mov_b32 m0, s38
	ds_read_b128 v[198:201], v179 offset:32768
	ds_read_b128 v[202:205], v179 offset:33792
	ds_read_b128 v[206:209], v179 offset:34816
	ds_read_b128 v[210:213], v179 offset:35840
	ds_read_b128 v[214:217], v179 offset:36864
	ds_read_b128 v[218:221], v179 offset:37888
	ds_read_b128 v[222:225], v179 offset:38912
	ds_read_b128 v[242:245], v179 offset:39936
	global_load_lds_dwordx4 v170, s[56:57]
	s_mov_b32 m0, s39
	s_nop 0
	global_load_lds_dwordx4 v166, s[56:57]
	s_waitcnt vmcnt(8)
	s_waitcnt lgkmcnt(0)
	s_barrier
	s_setprio 1
	v_mfma_f32_16x16x32_bf16 v[128:131], v[132:135], v[198:201], v[128:131]
	v_mfma_f32_16x16x32_bf16 v[124:127], v[140:143], v[198:201], v[124:127]
	v_mfma_f32_16x16x32_bf16 v[120:123], v[132:135], v[206:209], v[120:123]
	v_mfma_f32_16x16x32_bf16 v[116:119], v[140:143], v[206:209], v[116:119]
	v_mfma_f32_16x16x32_bf16 v[112:115], v[132:135], v[214:217], v[112:115]
	v_mfma_f32_16x16x32_bf16 v[108:111], v[140:143], v[214:217], v[108:111]
	v_mfma_f32_16x16x32_bf16 v[104:107], v[132:135], v[222:225], v[104:107]
	v_mfma_f32_16x16x32_bf16 v[100:103], v[140:143], v[222:225], v[100:103]
	v_mfma_f32_16x16x32_bf16 v[128:131], v[136:139], v[202:205], v[128:131]
	v_mfma_f32_16x16x32_bf16 v[124:127], v[144:147], v[202:205], v[124:127]
	v_mfma_f32_16x16x32_bf16 v[120:123], v[136:139], v[210:213], v[120:123]
	v_mfma_f32_16x16x32_bf16 v[116:119], v[144:147], v[210:213], v[116:119]
	v_mfma_f32_16x16x32_bf16 v[112:115], v[136:139], v[218:221], v[112:115]
	v_mfma_f32_16x16x32_bf16 v[108:111], v[144:147], v[218:221], v[108:111]
	v_mfma_f32_16x16x32_bf16 v[104:107], v[136:139], v[242:245], v[104:107]
	v_mfma_f32_16x16x32_bf16 v[100:103], v[144:147], v[242:245], v[100:103]
	s_setprio 0
	s_setprio 1
	v_mfma_f32_16x16x32_bf16 v[96:99], v[148:151], v[198:201], v[96:99]
	v_mfma_f32_16x16x32_bf16 v[92:95], v[156:159], v[198:201], v[92:95]
	v_mfma_f32_16x16x32_bf16 v[88:91], v[148:151], v[206:209], v[88:91]
	v_mfma_f32_16x16x32_bf16 v[84:87], v[156:159], v[206:209], v[84:87]
	v_mfma_f32_16x16x32_bf16 v[80:83], v[148:151], v[214:217], v[80:83]
	v_mfma_f32_16x16x32_bf16 v[76:79], v[156:159], v[214:217], v[76:79]
	v_mfma_f32_16x16x32_bf16 v[70:73], v[148:151], v[222:225], v[72:75]
	v_mfma_f32_16x16x32_bf16 v[66:69], v[156:159], v[222:225], v[66:69]
	v_mfma_f32_16x16x32_bf16 v[96:99], v[152:155], v[202:205], v[96:99]
	v_mfma_f32_16x16x32_bf16 v[92:95], v[160:163], v[202:205], v[92:95]
	v_mfma_f32_16x16x32_bf16 v[88:91], v[152:155], v[210:213], v[88:91]
	v_mfma_f32_16x16x32_bf16 v[84:87], v[160:163], v[210:213], v[84:87]
	v_mfma_f32_16x16x32_bf16 v[80:83], v[152:155], v[218:221], v[80:83]
	v_mfma_f32_16x16x32_bf16 v[76:79], v[160:163], v[218:221], v[76:79]
	v_mfma_f32_16x16x32_bf16 v[72:75], v[152:155], v[242:245], v[70:73]
	v_mfma_f32_16x16x32_bf16 v[68:71], v[160:163], v[242:245], v[66:69]
	s_setprio 0
	s_barrier
	s_add_i32 m0, s40, 0xffffff80
	s_add_u32 s58, s26, 0x80080
	s_addc_u32 s59, s27, 0
	ds_read_b128 v[198:201], v179 offset:49152
	ds_read_b128 v[202:205], v179 offset:50176
	ds_read_b128 v[206:209], v179 offset:51200
	ds_read_b128 v[210:213], v179 offset:52224
	ds_read_b128 v[214:217], v179 offset:53248
	ds_read_b128 v[218:221], v179 offset:54272
	ds_read_b128 v[222:225], v179 offset:55296
	ds_read_b128 v[242:245], v179 offset:56320
	global_load_lds_dwordx4 v168, s[26:27] offset:128
	s_add_i32 m0, s41, 0xffffff80
	s_nop 0
	global_load_lds_dwordx4 v164, s[26:27] offset:128
	s_mov_b32 m0, s44
	s_nop 0
	global_load_lds_dwordx4 v168, s[58:59]
	s_mov_b32 m0, s45
	s_nop 0
	global_load_lds_dwordx4 v164, s[58:59]
	s_add_i32 m0, s42, 0xffffff80
	s_nop 0
	global_load_lds_dwordx4 v170, s[28:29] offset:128
	s_add_i32 m0, s43, 0xffffff80
	s_nop 0
	global_load_lds_dwordx4 v166, s[28:29] offset:128
	s_waitcnt vmcnt(8)
	s_waitcnt lgkmcnt(0)
	s_barrier
	s_setprio 1
	v_mfma_f32_16x16x32_bf16 v[60:63], v[132:135], v[198:201], v[60:63]
	v_mfma_f32_16x16x32_bf16 v[56:59], v[140:143], v[198:201], v[56:59]
	v_mfma_f32_16x16x32_bf16 v[52:55], v[132:135], v[206:209], v[52:55]
	v_mfma_f32_16x16x32_bf16 v[48:51], v[140:143], v[206:209], v[48:51]
	v_mfma_f32_16x16x32_bf16 v[44:47], v[132:135], v[214:217], v[44:47]
	v_mfma_f32_16x16x32_bf16 v[40:43], v[140:143], v[214:217], v[40:43]
	v_mfma_f32_16x16x32_bf16 v[36:39], v[132:135], v[222:225], v[36:39]
	v_mfma_f32_16x16x32_bf16 v[32:35], v[140:143], v[222:225], v[32:35]
	v_mfma_f32_16x16x32_bf16 v[60:63], v[136:139], v[202:205], v[60:63]
	v_mfma_f32_16x16x32_bf16 v[56:59], v[144:147], v[202:205], v[56:59]
	v_mfma_f32_16x16x32_bf16 v[52:55], v[136:139], v[210:213], v[52:55]
	v_mfma_f32_16x16x32_bf16 v[48:51], v[144:147], v[210:213], v[48:51]
	v_mfma_f32_16x16x32_bf16 v[44:47], v[136:139], v[218:221], v[44:47]
	v_mfma_f32_16x16x32_bf16 v[40:43], v[144:147], v[218:221], v[40:43]
	v_mfma_f32_16x16x32_bf16 v[36:39], v[136:139], v[242:245], v[36:39]
	v_mfma_f32_16x16x32_bf16 v[32:35], v[144:147], v[242:245], v[32:35]
	s_setprio 0
	s_setprio 1
	v_mfma_f32_16x16x32_bf16 v[28:31], v[148:151], v[198:201], v[28:31]
	v_mfma_f32_16x16x32_bf16 v[24:27], v[156:159], v[198:201], v[24:27]
	v_mfma_f32_16x16x32_bf16 v[20:23], v[148:151], v[206:209], v[20:23]
	v_mfma_f32_16x16x32_bf16 v[16:19], v[156:159], v[206:209], v[16:19]
	v_mfma_f32_16x16x32_bf16 v[12:15], v[148:151], v[214:217], v[12:15]
	v_mfma_f32_16x16x32_bf16 v[8:11], v[156:159], v[214:217], v[8:11]
	v_mfma_f32_16x16x32_bf16 v[4:7], v[148:151], v[222:225], v[4:7]
	v_mfma_f32_16x16x32_bf16 v[0:3], v[156:159], v[222:225], v[0:3]
	v_mfma_f32_16x16x32_bf16 v[28:31], v[152:155], v[202:205], v[28:31]
	v_mfma_f32_16x16x32_bf16 v[24:27], v[160:163], v[202:205], v[24:27]
	v_mfma_f32_16x16x32_bf16 v[20:23], v[152:155], v[210:213], v[20:23]
	v_mfma_f32_16x16x32_bf16 v[16:19], v[160:163], v[210:213], v[16:19]
	v_mfma_f32_16x16x32_bf16 v[12:15], v[152:155], v[218:221], v[12:15]
	v_mfma_f32_16x16x32_bf16 v[8:11], v[160:163], v[218:221], v[8:11]
	v_mfma_f32_16x16x32_bf16 v[4:7], v[152:155], v[242:245], v[4:7]
	v_mfma_f32_16x16x32_bf16 v[0:3], v[160:163], v[242:245], v[0:3]
	s_add_u32 s22, s22, 0x100
	s_addc_u32 s23, s23, 0
	s_add_u32 s55, s55, 0x100
	s_addc_u32 s72, s72, 0
	s_cmp_ge_u32 s73, s13
	s_mov_b32 s28, s73
	s_setprio 0
	s_barrier
	s_cbranch_scc0 .LBB0_25
	s_and_b64 vcc, exec, s[10:11]
	s_cbranch_vccz .LBB0_28
	s_barrier

.LBB0_170:
	ds_read_b128 v[140:143], v220
	ds_read_b128 v[148:151], v220 offset:1024
	ds_read_b128 v[152:155], v220 offset:2048
	ds_read_b128 v[156:159], v220 offset:3072
	ds_read_b128 v[160:163], v220 offset:16384
	ds_read_b128 v[164:167], v220 offset:17408
	ds_read_b128 v[168:171], v220 offset:18432
	ds_read_b128 v[172:175], v220 offset:19456
	s_add_u32 s26, s24, 0xfff80080
	s_addc_u32 s27, s25, -1
	s_cmp_eq_u32 s51, 28
	s_cselect_b32 s29, s13, s27
	s_cselect_b32 s28, s47, s26
	s_cselect_b32 s27, s15, s50
	s_cselect_b32 s26, s48, s49
	s_add_i32 m0, s2, 0xc000
	ds_read_b128 v[176:179], v145
	ds_read_b128 v[180:183], v145 offset:1024
	ds_read_b128 v[184:187], v145 offset:2048
	ds_read_b128 v[188:191], v145 offset:3072
	ds_read_b128 v[196:199], v145 offset:4096
	ds_read_b128 v[200:203], v145 offset:5120
	ds_read_b128 v[204:207], v145 offset:6144
	ds_read_b128 v[208:211], v145 offset:7168
	global_load_lds_dwordx4 v136, s[24:25]
	s_add_i32 m0, s2, 0xe000
	s_nop 0
	global_load_lds_dwordx4 v138, s[24:25]
	s_waitcnt vmcnt(8)
	s_waitcnt lgkmcnt(0)
	s_barrier
	s_setprio 1
	v_mfma_f32_16x16x32_bf16 v[126:129], v[140:143], v[176:179], v[126:129]
	v_mfma_f32_16x16x32_bf16 v[122:125], v[152:155], v[176:179], v[122:125]
	v_mfma_f32_16x16x32_bf16 v[110:113], v[140:143], v[184:187], v[110:113]
	v_mfma_f32_16x16x32_bf16 v[102:105], v[152:155], v[184:187], v[102:105]
	v_mfma_f32_16x16x32_bf16 v[94:97], v[140:143], v[196:199], v[94:97]
	v_mfma_f32_16x16x32_bf16 v[86:89], v[152:155], v[196:199], v[86:89]
	v_mfma_f32_16x16x32_bf16 v[78:81], v[140:143], v[204:207], v[78:81]
	v_mfma_f32_16x16x32_bf16 v[70:73], v[152:155], v[204:207], v[70:73]
	v_mfma_f32_16x16x32_bf16 v[126:129], v[148:151], v[180:183], v[126:129]
	v_mfma_f32_16x16x32_bf16 v[122:125], v[156:159], v[180:183], v[122:125]
	v_mfma_f32_16x16x32_bf16 v[110:113], v[148:151], v[188:191], v[110:113]
	v_mfma_f32_16x16x32_bf16 v[102:105], v[156:159], v[188:191], v[102:105]
	v_mfma_f32_16x16x32_bf16 v[94:97], v[148:151], v[200:203], v[94:97]
	v_mfma_f32_16x16x32_bf16 v[86:89], v[156:159], v[200:203], v[86:89]
	v_mfma_f32_16x16x32_bf16 v[78:81], v[148:151], v[208:211], v[78:81]
	v_mfma_f32_16x16x32_bf16 v[70:73], v[156:159], v[208:211], v[70:73]
	s_setprio 0
	s_setprio 1
	v_mfma_f32_16x16x32_bf16 v[118:121], v[160:163], v[176:179], v[118:121]
	v_mfma_f32_16x16x32_bf16 v[114:117], v[168:171], v[176:179], v[114:117]
	v_mfma_f32_16x16x32_bf16 v[106:109], v[160:163], v[184:187], v[106:109]
	v_mfma_f32_16x16x32_bf16 v[98:101], v[168:171], v[184:187], v[98:101]
	v_mfma_f32_16x16x32_bf16 v[90:93], v[160:163], v[196:199], v[90:93]
	v_mfma_f32_16x16x32_bf16 v[82:85], v[168:171], v[196:199], v[82:85]
	v_mfma_f32_16x16x32_bf16 v[74:77], v[160:163], v[204:207], v[74:77]
	v_mfma_f32_16x16x32_bf16 v[66:69], v[168:171], v[204:207], v[66:69]
	v_mfma_f32_16x16x32_bf16 v[118:121], v[164:167], v[180:183], v[118:121]
	v_mfma_f32_16x16x32_bf16 v[114:117], v[172:175], v[180:183], v[114:117]
	v_mfma_f32_16x16x32_bf16 v[106:109], v[164:167], v[188:191], v[106:109]
	v_mfma_f32_16x16x32_bf16 v[98:101], v[172:175], v[188:191], v[98:101]
	v_mfma_f32_16x16x32_bf16 v[90:93], v[164:167], v[200:203], v[90:93]
	v_mfma_f32_16x16x32_bf16 v[82:85], v[172:175], v[200:203], v[82:85]
	v_mfma_f32_16x16x32_bf16 v[74:77], v[164:167], v[208:211], v[74:77]
	v_mfma_f32_16x16x32_bf16 v[66:69], v[172:175], v[208:211], v[66:69]
	s_setprio 0
	s_barrier
	s_mov_b32 m0, s5
	s_add_u32 s52, s26, 0x80000
	s_addc_u32 s53, s27, 0
	ds_read_b128 v[176:179], v145 offset:16384
	ds_read_b128 v[180:183], v145 offset:17408
	ds_read_b128 v[184:187], v145 offset:18432
	ds_read_b128 v[188:191], v145 offset:19456
	ds_read_b128 v[196:199], v145 offset:20480
	ds_read_b128 v[200:203], v145 offset:21504
	ds_read_b128 v[204:207], v145 offset:22528
	ds_read_b128 v[208:211], v145 offset:23552
	global_load_lds_dwordx4 v64, s[26:27]
	s_mov_b32 m0, s30
	s_nop 0
	global_load_lds_dwordx4 v130, s[26:27]
	s_mov_b32 m0, s31
	s_nop 0
	global_load_lds_dwordx4 v64, s[52:53]
	s_mov_b32 m0, s34
	s_nop 0
	global_load_lds_dwordx4 v130, s[52:53]
	s_mov_b32 m0, s2
	s_nop 0
	global_load_lds_dwordx4 v134, s[28:29]
	s_mov_b32 m0, s35
	s_nop 0
	global_load_lds_dwordx4 v132, s[28:29]
	s_waitcnt vmcnt(8)
	s_waitcnt lgkmcnt(0)
	s_barrier
	s_setprio 1
	v_mfma_f32_16x16x32_bf16 v[60:63], v[140:143], v[176:179], v[60:63]
	v_mfma_f32_16x16x32_bf16 v[52:55], v[152:155], v[176:179], v[52:55]
	v_mfma_f32_16x16x32_bf16 v[44:47], v[140:143], v[184:187], v[44:47]
	v_mfma_f32_16x16x32_bf16 v[36:39], v[152:155], v[184:187], v[36:39]
	v_mfma_f32_16x16x32_bf16 v[28:31], v[140:143], v[196:199], v[28:31]
	v_mfma_f32_16x16x32_bf16 v[20:23], v[152:155], v[196:199], v[20:23]
	v_mfma_f32_16x16x32_bf16 v[12:15], v[140:143], v[204:207], v[12:15]
	v_mfma_f32_16x16x32_bf16 v[4:7], v[152:155], v[204:207], v[4:7]
	v_mfma_f32_16x16x32_bf16 v[60:63], v[148:151], v[180:183], v[60:63]
	v_mfma_f32_16x16x32_bf16 v[52:55], v[156:159], v[180:183], v[52:55]
	v_mfma_f32_16x16x32_bf16 v[44:47], v[148:151], v[188:191], v[44:47]
	v_mfma_f32_16x16x32_bf16 v[36:39], v[156:159], v[188:191], v[36:39]
	v_mfma_f32_16x16x32_bf16 v[28:31], v[148:151], v[200:203], v[28:31]
	v_mfma_f32_16x16x32_bf16 v[20:23], v[156:159], v[200:203], v[20:23]
	v_mfma_f32_16x16x32_bf16 v[12:15], v[148:151], v[208:211], v[12:15]
	v_mfma_f32_16x16x32_bf16 v[4:7], v[156:159], v[208:211], v[4:7]
	s_setprio 0
	s_setprio 1
	v_mfma_f32_16x16x32_bf16 v[56:59], v[160:163], v[176:179], v[56:59]
	v_mfma_f32_16x16x32_bf16 v[48:51], v[168:171], v[176:179], v[48:51]
	v_mfma_f32_16x16x32_bf16 v[40:43], v[160:163], v[184:187], v[40:43]
	v_mfma_f32_16x16x32_bf16 v[32:35], v[168:171], v[184:187], v[32:35]
	v_mfma_f32_16x16x32_bf16 v[24:27], v[160:163], v[196:199], v[24:27]
	v_mfma_f32_16x16x32_bf16 v[16:19], v[168:171], v[196:199], v[16:19]
	v_mfma_f32_16x16x32_bf16 v[8:11], v[160:163], v[204:207], v[8:11]
	v_mfma_f32_16x16x32_bf16 v[0:3], v[168:171], v[204:207], v[0:3]
	v_mfma_f32_16x16x32_bf16 v[56:59], v[164:167], v[180:183], v[56:59]
	v_mfma_f32_16x16x32_bf16 v[48:51], v[172:175], v[180:183], v[48:51]
	v_mfma_f32_16x16x32_bf16 v[40:43], v[164:167], v[188:191], v[40:43]
	v_mfma_f32_16x16x32_bf16 v[32:35], v[172:175], v[188:191], v[32:35]
	v_mfma_f32_16x16x32_bf16 v[24:27], v[164:167], v[200:203], v[24:27]
	v_mfma_f32_16x16x32_bf16 v[16:19], v[172:175], v[200:203], v[16:19]
	v_mfma_f32_16x16x32_bf16 v[8:11], v[164:167], v[208:211], v[8:11]
	v_mfma_f32_16x16x32_bf16 v[0:3], v[172:175], v[208:211], v[0:3]
	s_setprio 0
	s_barrier
	ds_read_b128 v[140:143], v220 offset:32768
	ds_read_b128 v[148:151], v220 offset:33792
	ds_read_b128 v[152:155], v220 offset:34816
	ds_read_b128 v[156:159], v220 offset:35840
	ds_read_b128 v[160:163], v220 offset:49152
	ds_read_b128 v[164:167], v220 offset:50176
	ds_read_b128 v[168:171], v220 offset:51200
	ds_read_b128 v[172:175], v220 offset:52224
	s_add_u32 s56, s28, 0x80000
	s_addc_u32 s57, s29, 0
	s_mov_b32 m0, s36
	ds_read_b128 v[176:179], v145 offset:32768
	ds_read_b128 v[180:183], v145 offset:33792
	ds_read_b128 v[184:187], v145 offset:34816
	ds_read_b128 v[188:191], v145 offset:35840
	ds_read_b128 v[196:199], v145 offset:36864
	ds_read_b128 v[200:203], v145 offset:37888
	ds_read_b128 v[204:207], v145 offset:38912
	ds_read_b128 v[208:211], v145 offset:39936
	global_load_lds_dwordx4 v134, s[56:57]
	s_mov_b32 m0, s37
	s_nop 0
	global_load_lds_dwordx4 v132, s[56:57]
	s_waitcnt vmcnt(8)
	s_waitcnt lgkmcnt(0)
	s_barrier
	s_setprio 1
	v_mfma_f32_16x16x32_bf16 v[126:129], v[140:143], v[176:179], v[126:129]
	v_mfma_f32_16x16x32_bf16 v[122:125], v[152:155], v[176:179], v[122:125]
	v_mfma_f32_16x16x32_bf16 v[110:113], v[140:143], v[184:187], v[110:113]
	v_mfma_f32_16x16x32_bf16 v[102:105], v[152:155], v[184:187], v[102:105]
	v_mfma_f32_16x16x32_bf16 v[94:97], v[140:143], v[196:199], v[94:97]
	v_mfma_f32_16x16x32_bf16 v[86:89], v[152:155], v[196:199], v[86:89]
	v_mfma_f32_16x16x32_bf16 v[78:81], v[140:143], v[204:207], v[78:81]
	v_mfma_f32_16x16x32_bf16 v[70:73], v[152:155], v[204:207], v[70:73]
	v_mfma_f32_16x16x32_bf16 v[126:129], v[148:151], v[180:183], v[126:129]
	v_mfma_f32_16x16x32_bf16 v[122:125], v[156:159], v[180:183], v[122:125]
	v_mfma_f32_16x16x32_bf16 v[110:113], v[148:151], v[188:191], v[110:113]
	v_mfma_f32_16x16x32_bf16 v[102:105], v[156:159], v[188:191], v[102:105]
	v_mfma_f32_16x16x32_bf16 v[94:97], v[148:151], v[200:203], v[94:97]
	v_mfma_f32_16x16x32_bf16 v[86:89], v[156:159], v[200:203], v[86:89]
	v_mfma_f32_16x16x32_bf16 v[78:81], v[148:151], v[208:211], v[78:81]
	v_mfma_f32_16x16x32_bf16 v[70:73], v[156:159], v[208:211], v[70:73]
	s_setprio 0
	s_setprio 1
	v_mfma_f32_16x16x32_bf16 v[118:121], v[160:163], v[176:179], v[118:121]
	v_mfma_f32_16x16x32_bf16 v[114:117], v[168:171], v[176:179], v[114:117]
	v_mfma_f32_16x16x32_bf16 v[106:109], v[160:163], v[184:187], v[106:109]
	v_mfma_f32_16x16x32_bf16 v[98:101], v[168:171], v[184:187], v[98:101]
	v_mfma_f32_16x16x32_bf16 v[90:93], v[160:163], v[196:199], v[90:93]
	v_mfma_f32_16x16x32_bf16 v[82:85], v[168:171], v[196:199], v[82:85]
	v_mfma_f32_16x16x32_bf16 v[74:77], v[160:163], v[204:207], v[74:77]
	v_mfma_f32_16x16x32_bf16 v[66:69], v[168:171], v[204:207], v[66:69]
	v_mfma_f32_16x16x32_bf16 v[118:121], v[164:167], v[180:183], v[118:121]
	v_mfma_f32_16x16x32_bf16 v[114:117], v[172:175], v[180:183], v[114:117]
	v_mfma_f32_16x16x32_bf16 v[106:109], v[164:167], v[188:191], v[106:109]
	v_mfma_f32_16x16x32_bf16 v[98:101], v[172:175], v[188:191], v[98:101]
	v_mfma_f32_16x16x32_bf16 v[90:93], v[164:167], v[200:203], v[90:93]
	v_mfma_f32_16x16x32_bf16 v[82:85], v[172:175], v[200:203], v[82:85]
	v_mfma_f32_16x16x32_bf16 v[74:77], v[164:167], v[208:211], v[74:77]
	v_mfma_f32_16x16x32_bf16 v[66:69], v[172:175], v[208:211], v[66:69]
	s_setprio 0
	s_barrier
	s_add_i32 m0, s38, 0xffffff80
	s_add_u32 s58, s26, 0x80080
	s_addc_u32 s59, s27, 0
	ds_read_b128 v[176:179], v145 offset:49152
	ds_read_b128 v[180:183], v145 offset:50176
	ds_read_b128 v[184:187], v145 offset:51200
	ds_read_b128 v[188:191], v145 offset:52224
	ds_read_b128 v[196:199], v145 offset:53248
	ds_read_b128 v[200:203], v145 offset:54272
	ds_read_b128 v[204:207], v145 offset:55296
	ds_read_b128 v[208:211], v145 offset:56320
	global_load_lds_dwordx4 v64, s[26:27] offset:128
	s_add_i32 m0, s39, 0xffffff80
	s_nop 0
	global_load_lds_dwordx4 v130, s[26:27] offset:128
	s_mov_b32 m0, s42
	s_nop 0
	global_load_lds_dwordx4 v64, s[58:59]
	s_mov_b32 m0, s43
	s_nop 0
	global_load_lds_dwordx4 v130, s[58:59]
	s_add_i32 m0, s40, 0xffffff80
	s_nop 0
	global_load_lds_dwordx4 v134, s[28:29] offset:128
	s_add_i32 m0, s41, 0xffffff80
	s_nop 0
	global_load_lds_dwordx4 v132, s[28:29] offset:128
	s_waitcnt vmcnt(8)
	s_waitcnt lgkmcnt(0)
	s_barrier
	s_setprio 1
	v_mfma_f32_16x16x32_bf16 v[60:63], v[140:143], v[176:179], v[60:63]
	v_mfma_f32_16x16x32_bf16 v[52:55], v[152:155], v[176:179], v[52:55]
	v_mfma_f32_16x16x32_bf16 v[44:47], v[140:143], v[184:187], v[44:47]
	v_mfma_f32_16x16x32_bf16 v[36:39], v[152:155], v[184:187], v[36:39]
	v_mfma_f32_16x16x32_bf16 v[28:31], v[140:143], v[196:199], v[28:31]
	v_mfma_f32_16x16x32_bf16 v[20:23], v[152:155], v[196:199], v[20:23]
	v_mfma_f32_16x16x32_bf16 v[12:15], v[140:143], v[204:207], v[12:15]
	v_mfma_f32_16x16x32_bf16 v[4:7], v[152:155], v[204:207], v[4:7]
	v_mfma_f32_16x16x32_bf16 v[60:63], v[148:151], v[180:183], v[60:63]
	v_mfma_f32_16x16x32_bf16 v[52:55], v[156:159], v[180:183], v[52:55]
	v_mfma_f32_16x16x32_bf16 v[44:47], v[148:151], v[188:191], v[44:47]
	v_mfma_f32_16x16x32_bf16 v[36:39], v[156:159], v[188:191], v[36:39]
	v_mfma_f32_16x16x32_bf16 v[28:31], v[148:151], v[200:203], v[28:31]
	v_mfma_f32_16x16x32_bf16 v[20:23], v[156:159], v[200:203], v[20:23]
	v_mfma_f32_16x16x32_bf16 v[12:15], v[148:151], v[208:211], v[12:15]
	v_mfma_f32_16x16x32_bf16 v[4:7], v[156:159], v[208:211], v[4:7]
	s_setprio 0
	s_setprio 1
	v_mfma_f32_16x16x32_bf16 v[56:59], v[160:163], v[176:179], v[56:59]
	v_mfma_f32_16x16x32_bf16 v[48:51], v[168:171], v[176:179], v[48:51]
	v_mfma_f32_16x16x32_bf16 v[40:43], v[160:163], v[184:187], v[40:43]
	v_mfma_f32_16x16x32_bf16 v[32:35], v[168:171], v[184:187], v[32:35]
	v_mfma_f32_16x16x32_bf16 v[24:27], v[160:163], v[196:199], v[24:27]
	v_mfma_f32_16x16x32_bf16 v[16:19], v[168:171], v[196:199], v[16:19]
	v_mfma_f32_16x16x32_bf16 v[8:11], v[160:163], v[204:207], v[8:11]
	v_mfma_f32_16x16x32_bf16 v[0:3], v[168:171], v[204:207], v[0:3]
	v_mfma_f32_16x16x32_bf16 v[56:59], v[164:167], v[180:183], v[56:59]
	v_mfma_f32_16x16x32_bf16 v[48:51], v[172:175], v[180:183], v[48:51]
	v_mfma_f32_16x16x32_bf16 v[40:43], v[164:167], v[188:191], v[40:43]
	v_mfma_f32_16x16x32_bf16 v[32:35], v[172:175], v[188:191], v[32:35]
	v_mfma_f32_16x16x32_bf16 v[24:27], v[164:167], v[200:203], v[24:27]
	v_mfma_f32_16x16x32_bf16 v[16:19], v[172:175], v[200:203], v[16:19]
	v_mfma_f32_16x16x32_bf16 v[8:11], v[164:167], v[208:211], v[8:11]
	v_mfma_f32_16x16x32_bf16 v[0:3], v[172:175], v[208:211], v[0:3]
	s_add_i32 s51, s51, 2
	s_add_u32 s24, s24, 0x100
	s_addc_u32 s25, s25, 0
	s_add_u32 s49, s49, 0x100
	s_addc_u32 s50, s50, 0
	s_cmp_gt_u32 s51, 29
	s_setprio 0
	s_barrier
	s_cbranch_scc0 .LBB0_170
	s_and_b64 vcc, exec, s[10:11]
	s_cbranch_vccz .LBB0_173
	s_barrier

.LBB0_201:
	s_add_i32 s48, s12, 2
	ds_read_b128 v[130:133], v252
	ds_read_b128 v[134:137], v252 offset:1024
	ds_read_b128 v[138:141], v252 offset:2048
	ds_read_b128 v[142:145], v252 offset:3072
	ds_read_b128 v[146:149], v252 offset:16384
	ds_read_b128 v[150:153], v252 offset:17408
	ds_read_b128 v[154:157], v252 offset:18432
	ds_read_b128 v[158:161], v252 offset:19456
	s_add_u32 s49, s10, 0x80
	s_addc_u32 s13, s11, 0
	s_cmp_eq_u32 s73, s12
	s_cselect_b32 s12, s44, s49
	s_cselect_b32 s13, s45, s13
	s_cselect_b32 s77, s47, s15
	s_cselect_b32 s76, s46, s14
	s_add_i32 m0, s5, 0xc000
	ds_read_b128 v[162:165], v241
	ds_read_b128 v[166:169], v241 offset:1024
	ds_read_b128 v[170:173], v241 offset:2048
	ds_read_b128 v[174:177], v241 offset:3072
	ds_read_b128 v[178:181], v241 offset:4096
	ds_read_b128 v[182:185], v241 offset:5120
	ds_read_b128 v[186:189], v241 offset:6144
	ds_read_b128 v[190:193], v241 offset:7168
	global_load_lds_dwordx4 v202, s[10:11]
	s_add_i32 m0, s5, 0xe000
	s_nop 0
	global_load_lds_dwordx4 v204, s[10:11]
	s_waitcnt vmcnt(8)
	s_waitcnt lgkmcnt(0)
	s_barrier
	s_setprio 1
	v_mfma_f32_16x16x32_bf16 v[126:129], v[130:133], v[162:165], v[126:129]
	v_mfma_f32_16x16x32_bf16 v[122:125], v[138:141], v[162:165], v[122:125]
	v_mfma_f32_16x16x32_bf16 v[110:113], v[130:133], v[170:173], v[110:113]
	v_mfma_f32_16x16x32_bf16 v[106:109], v[138:141], v[170:173], v[106:109]
	v_mfma_f32_16x16x32_bf16 v[94:97], v[130:133], v[178:181], v[94:97]
	v_mfma_f32_16x16x32_bf16 v[90:93], v[138:141], v[178:181], v[90:93]
	v_mfma_f32_16x16x32_bf16 v[78:81], v[130:133], v[186:189], v[78:81]
	v_mfma_f32_16x16x32_bf16 v[74:77], v[138:141], v[186:189], v[74:77]
	v_mfma_f32_16x16x32_bf16 v[126:129], v[134:137], v[166:169], v[126:129]
	v_mfma_f32_16x16x32_bf16 v[122:125], v[142:145], v[166:169], v[122:125]
	v_mfma_f32_16x16x32_bf16 v[110:113], v[134:137], v[174:177], v[110:113]
	v_mfma_f32_16x16x32_bf16 v[106:109], v[142:145], v[174:177], v[106:109]
	v_mfma_f32_16x16x32_bf16 v[94:97], v[134:137], v[182:185], v[94:97]
	v_mfma_f32_16x16x32_bf16 v[90:93], v[142:145], v[182:185], v[90:93]
	v_mfma_f32_16x16x32_bf16 v[78:81], v[134:137], v[190:193], v[78:81]
	v_mfma_f32_16x16x32_bf16 v[74:77], v[142:145], v[190:193], v[74:77]
	s_setprio 0
	s_setprio 1
	v_mfma_f32_16x16x32_bf16 v[118:121], v[146:149], v[162:165], v[118:121]
	v_mfma_f32_16x16x32_bf16 v[114:117], v[154:157], v[162:165], v[114:117]
	v_mfma_f32_16x16x32_bf16 v[102:105], v[146:149], v[170:173], v[102:105]
	v_mfma_f32_16x16x32_bf16 v[98:101], v[154:157], v[170:173], v[98:101]
	v_mfma_f32_16x16x32_bf16 v[86:89], v[146:149], v[178:181], v[86:89]
	v_mfma_f32_16x16x32_bf16 v[82:85], v[154:157], v[178:181], v[82:85]
	v_mfma_f32_16x16x32_bf16 v[70:73], v[146:149], v[186:189], v[70:73]
	v_mfma_f32_16x16x32_bf16 v[66:69], v[154:157], v[186:189], v[66:69]
	v_mfma_f32_16x16x32_bf16 v[118:121], v[150:153], v[166:169], v[118:121]
	v_mfma_f32_16x16x32_bf16 v[114:117], v[158:161], v[166:169], v[114:117]
	v_mfma_f32_16x16x32_bf16 v[102:105], v[150:153], v[174:177], v[102:105]
	v_mfma_f32_16x16x32_bf16 v[98:101], v[158:161], v[174:177], v[98:101]
	v_mfma_f32_16x16x32_bf16 v[86:89], v[150:153], v[182:185], v[86:89]
	v_mfma_f32_16x16x32_bf16 v[82:85], v[158:161], v[182:185], v[82:85]
	v_mfma_f32_16x16x32_bf16 v[70:73], v[150:153], v[190:193], v[70:73]
	v_mfma_f32_16x16x32_bf16 v[66:69], v[158:161], v[190:193], v[66:69]
	s_setprio 0
	s_barrier
	s_mov_b32 m0, s52
	s_add_u32 s58, s76, s0
	s_addc_u32 s59, s77, 0
	ds_read_b128 v[162:165], v241 offset:16384
	ds_read_b128 v[166:169], v241 offset:17408
	ds_read_b128 v[170:173], v241 offset:18432
	ds_read_b128 v[174:177], v241 offset:19456
	ds_read_b128 v[178:181], v241 offset:20480
	ds_read_b128 v[182:185], v241 offset:21504
	ds_read_b128 v[186:189], v241 offset:22528
	ds_read_b128 v[190:193], v241 offset:23552
	global_load_lds_dwordx4 v64, s[76:77]
	s_mov_b32 m0, s53
	s_nop 0
	global_load_lds_dwordx4 v196, s[76:77]
	s_mov_b32 m0, s54
	s_nop 0
	global_load_lds_dwordx4 v64, s[58:59]
	s_mov_b32 m0, s55
	s_nop 0
	global_load_lds_dwordx4 v196, s[58:59]
	s_mov_b32 m0, s5
	s_nop 0
	global_load_lds_dwordx4 v200, s[12:13]
	s_mov_b32 m0, s87
	s_nop 0
	global_load_lds_dwordx4 v198, s[12:13]
	s_waitcnt vmcnt(8)
	s_waitcnt lgkmcnt(0)
	s_barrier
	s_setprio 1
	v_mfma_f32_16x16x32_bf16 v[60:63], v[130:133], v[162:165], v[60:63]
	v_mfma_f32_16x16x32_bf16 v[56:59], v[138:141], v[162:165], v[56:59]
	v_mfma_f32_16x16x32_bf16 v[44:47], v[130:133], v[170:173], v[44:47]
	v_mfma_f32_16x16x32_bf16 v[40:43], v[138:141], v[170:173], v[40:43]
	v_mfma_f32_16x16x32_bf16 v[28:31], v[130:133], v[178:181], v[28:31]
	v_mfma_f32_16x16x32_bf16 v[24:27], v[138:141], v[178:181], v[24:27]
	v_mfma_f32_16x16x32_bf16 v[12:15], v[130:133], v[186:189], v[12:15]
	v_mfma_f32_16x16x32_bf16 v[8:11], v[138:141], v[186:189], v[8:11]
	v_mfma_f32_16x16x32_bf16 v[60:63], v[134:137], v[166:169], v[60:63]
	v_mfma_f32_16x16x32_bf16 v[56:59], v[142:145], v[166:169], v[56:59]
	v_mfma_f32_16x16x32_bf16 v[44:47], v[134:137], v[174:177], v[44:47]
	v_mfma_f32_16x16x32_bf16 v[40:43], v[142:145], v[174:177], v[40:43]
	v_mfma_f32_16x16x32_bf16 v[28:31], v[134:137], v[182:185], v[28:31]
	v_mfma_f32_16x16x32_bf16 v[24:27], v[142:145], v[182:185], v[24:27]
	v_mfma_f32_16x16x32_bf16 v[12:15], v[134:137], v[190:193], v[12:15]
	v_mfma_f32_16x16x32_bf16 v[8:11], v[142:145], v[190:193], v[8:11]
	s_setprio 0
	s_setprio 1
	v_mfma_f32_16x16x32_bf16 v[52:55], v[146:149], v[162:165], v[52:55]
	v_mfma_f32_16x16x32_bf16 v[48:51], v[154:157], v[162:165], v[48:51]
	v_mfma_f32_16x16x32_bf16 v[36:39], v[146:149], v[170:173], v[36:39]
	v_mfma_f32_16x16x32_bf16 v[32:35], v[154:157], v[170:173], v[32:35]
	v_mfma_f32_16x16x32_bf16 v[20:23], v[146:149], v[178:181], v[20:23]
	v_mfma_f32_16x16x32_bf16 v[16:19], v[154:157], v[178:181], v[16:19]
	v_mfma_f32_16x16x32_bf16 v[4:7], v[146:149], v[186:189], v[4:7]
	v_mfma_f32_16x16x32_bf16 v[0:3], v[154:157], v[186:189], v[0:3]
	v_mfma_f32_16x16x32_bf16 v[52:55], v[150:153], v[166:169], v[52:55]
	v_mfma_f32_16x16x32_bf16 v[48:51], v[158:161], v[166:169], v[48:51]
	v_mfma_f32_16x16x32_bf16 v[36:39], v[150:153], v[174:177], v[36:39]
	v_mfma_f32_16x16x32_bf16 v[32:35], v[158:161], v[174:177], v[32:35]
	v_mfma_f32_16x16x32_bf16 v[20:23], v[150:153], v[182:185], v[20:23]
	v_mfma_f32_16x16x32_bf16 v[16:19], v[158:161], v[182:185], v[16:19]
	v_mfma_f32_16x16x32_bf16 v[4:7], v[150:153], v[190:193], v[4:7]
	v_mfma_f32_16x16x32_bf16 v[0:3], v[158:161], v[190:193], v[0:3]
	s_setprio 0
	s_barrier
	ds_read_b128 v[130:133], v252 offset:32768
	ds_read_b128 v[134:137], v252 offset:33792
	ds_read_b128 v[138:141], v252 offset:34816
	ds_read_b128 v[142:145], v252 offset:35840
	ds_read_b128 v[146:149], v252 offset:49152
	ds_read_b128 v[150:153], v252 offset:50176
	ds_read_b128 v[154:157], v252 offset:51200
	ds_read_b128 v[158:161], v252 offset:52224
	s_add_u32 s60, s12, s92
	s_addc_u32 s61, s13, 0
	s_mov_b32 m0, s88
	ds_read_b128 v[162:165], v241 offset:32768
	ds_read_b128 v[166:169], v241 offset:33792
	ds_read_b128 v[170:173], v241 offset:34816
	ds_read_b128 v[174:177], v241 offset:35840
	ds_read_b128 v[178:181], v241 offset:36864
	ds_read_b128 v[182:185], v241 offset:37888
	ds_read_b128 v[186:189], v241 offset:38912
	ds_read_b128 v[190:193], v241 offset:39936
	global_load_lds_dwordx4 v200, s[60:61]
	s_mov_b32 m0, s90
	s_nop 0
	global_load_lds_dwordx4 v198, s[60:61]
	s_waitcnt vmcnt(8)
	s_waitcnt lgkmcnt(0)
	s_barrier
	s_setprio 1
	v_mfma_f32_16x16x32_bf16 v[126:129], v[130:133], v[162:165], v[126:129]
	v_mfma_f32_16x16x32_bf16 v[122:125], v[138:141], v[162:165], v[122:125]
	v_mfma_f32_16x16x32_bf16 v[110:113], v[130:133], v[170:173], v[110:113]
	v_mfma_f32_16x16x32_bf16 v[106:109], v[138:141], v[170:173], v[106:109]
	v_mfma_f32_16x16x32_bf16 v[94:97], v[130:133], v[178:181], v[94:97]
	v_mfma_f32_16x16x32_bf16 v[90:93], v[138:141], v[178:181], v[90:93]
	v_mfma_f32_16x16x32_bf16 v[78:81], v[130:133], v[186:189], v[78:81]
	v_mfma_f32_16x16x32_bf16 v[74:77], v[138:141], v[186:189], v[74:77]
	v_mfma_f32_16x16x32_bf16 v[126:129], v[134:137], v[166:169], v[126:129]
	v_mfma_f32_16x16x32_bf16 v[122:125], v[142:145], v[166:169], v[122:125]
	v_mfma_f32_16x16x32_bf16 v[110:113], v[134:137], v[174:177], v[110:113]
	v_mfma_f32_16x16x32_bf16 v[106:109], v[142:145], v[174:177], v[106:109]
	v_mfma_f32_16x16x32_bf16 v[94:97], v[134:137], v[182:185], v[94:97]
	v_mfma_f32_16x16x32_bf16 v[90:93], v[142:145], v[182:185], v[90:93]
	v_mfma_f32_16x16x32_bf16 v[78:81], v[134:137], v[190:193], v[78:81]
	v_mfma_f32_16x16x32_bf16 v[74:77], v[142:145], v[190:193], v[74:77]
	s_setprio 0
	s_setprio 1
	v_mfma_f32_16x16x32_bf16 v[118:121], v[146:149], v[162:165], v[118:121]
	v_mfma_f32_16x16x32_bf16 v[114:117], v[154:157], v[162:165], v[114:117]
	v_mfma_f32_16x16x32_bf16 v[102:105], v[146:149], v[170:173], v[102:105]
	v_mfma_f32_16x16x32_bf16 v[98:101], v[154:157], v[170:173], v[98:101]
	v_mfma_f32_16x16x32_bf16 v[86:89], v[146:149], v[178:181], v[86:89]
	v_mfma_f32_16x16x32_bf16 v[82:85], v[154:157], v[178:181], v[82:85]
	v_mfma_f32_16x16x32_bf16 v[70:73], v[146:149], v[186:189], v[70:73]
	v_mfma_f32_16x16x32_bf16 v[66:69], v[154:157], v[186:189], v[66:69]
	v_mfma_f32_16x16x32_bf16 v[118:121], v[150:153], v[166:169], v[118:121]
	v_mfma_f32_16x16x32_bf16 v[114:117], v[158:161], v[166:169], v[114:117]
	v_mfma_f32_16x16x32_bf16 v[102:105], v[150:153], v[174:177], v[102:105]
	v_mfma_f32_16x16x32_bf16 v[98:101], v[158:161], v[174:177], v[98:101]
	v_mfma_f32_16x16x32_bf16 v[86:89], v[150:153], v[182:185], v[86:89]
	v_mfma_f32_16x16x32_bf16 v[82:85], v[158:161], v[182:185], v[82:85]
	v_mfma_f32_16x16x32_bf16 v[70:73], v[150:153], v[190:193], v[70:73]
	v_mfma_f32_16x16x32_bf16 v[66:69], v[158:161], v[190:193], v[66:69]
	s_setprio 0
	s_barrier
	s_add_i32 m0, s78, 0xffffff80
	ds_read_b128 v[162:165], v241 offset:49152
	ds_read_b128 v[166:169], v241 offset:50176
	ds_read_b128 v[170:173], v241 offset:51200
	ds_read_b128 v[174:177], v241 offset:52224
	ds_read_b128 v[178:181], v241 offset:53248
	ds_read_b128 v[182:185], v241 offset:54272
	ds_read_b128 v[186:189], v241 offset:55296
	ds_read_b128 v[190:193], v241 offset:56320
	global_load_lds_dwordx4 v64, s[76:77] offset:128
	s_add_i32 m0, s79, 0xffffff80
	s_nop 0
	global_load_lds_dwordx4 v196, s[76:77] offset:128
	s_add_i32 m0, s50, 0xffffff80
	s_nop 0
	global_load_lds_dwordx4 v64, s[58:59] offset:128
	s_add_i32 m0, s51, 0xffffff80
	s_nop 0
	global_load_lds_dwordx4 v196, s[58:59] offset:128
	s_add_i32 m0, s22, 0xffffff80
	s_nop 0
	global_load_lds_dwordx4 v200, s[12:13] offset:128
	s_add_i32 m0, s23, 0xffffff80
	s_nop 0
	global_load_lds_dwordx4 v198, s[12:13] offset:128
	s_waitcnt vmcnt(8)
	s_waitcnt lgkmcnt(0)
	s_barrier
	s_setprio 1
	v_mfma_f32_16x16x32_bf16 v[60:63], v[130:133], v[162:165], v[60:63]
	v_mfma_f32_16x16x32_bf16 v[56:59], v[138:141], v[162:165], v[56:59]
	v_mfma_f32_16x16x32_bf16 v[44:47], v[130:133], v[170:173], v[44:47]
	v_mfma_f32_16x16x32_bf16 v[40:43], v[138:141], v[170:173], v[40:43]
	v_mfma_f32_16x16x32_bf16 v[28:31], v[130:133], v[178:181], v[28:31]
	v_mfma_f32_16x16x32_bf16 v[24:27], v[138:141], v[178:181], v[24:27]
	v_mfma_f32_16x16x32_bf16 v[12:15], v[130:133], v[186:189], v[12:15]
	v_mfma_f32_16x16x32_bf16 v[8:11], v[138:141], v[186:189], v[8:11]
	v_mfma_f32_16x16x32_bf16 v[60:63], v[134:137], v[166:169], v[60:63]
	v_mfma_f32_16x16x32_bf16 v[56:59], v[142:145], v[166:169], v[56:59]
	v_mfma_f32_16x16x32_bf16 v[44:47], v[134:137], v[174:177], v[44:47]
	v_mfma_f32_16x16x32_bf16 v[40:43], v[142:145], v[174:177], v[40:43]
	v_mfma_f32_16x16x32_bf16 v[28:31], v[134:137], v[182:185], v[28:31]
	v_mfma_f32_16x16x32_bf16 v[24:27], v[142:145], v[182:185], v[24:27]
	v_mfma_f32_16x16x32_bf16 v[12:15], v[134:137], v[190:193], v[12:15]
	v_mfma_f32_16x16x32_bf16 v[8:11], v[142:145], v[190:193], v[8:11]
	s_setprio 0
	s_setprio 1
	v_mfma_f32_16x16x32_bf16 v[52:55], v[146:149], v[162:165], v[52:55]
	v_mfma_f32_16x16x32_bf16 v[48:51], v[154:157], v[162:165], v[48:51]
	v_mfma_f32_16x16x32_bf16 v[36:39], v[146:149], v[170:173], v[36:39]
	v_mfma_f32_16x16x32_bf16 v[32:35], v[154:157], v[170:173], v[32:35]
	v_mfma_f32_16x16x32_bf16 v[20:23], v[146:149], v[178:181], v[20:23]
	v_mfma_f32_16x16x32_bf16 v[16:19], v[154:157], v[178:181], v[16:19]
	v_mfma_f32_16x16x32_bf16 v[4:7], v[146:149], v[186:189], v[4:7]
	v_mfma_f32_16x16x32_bf16 v[0:3], v[154:157], v[186:189], v[0:3]
	v_mfma_f32_16x16x32_bf16 v[52:55], v[150:153], v[166:169], v[52:55]
	v_mfma_f32_16x16x32_bf16 v[48:51], v[158:161], v[166:169], v[48:51]
	v_mfma_f32_16x16x32_bf16 v[36:39], v[150:153], v[174:177], v[36:39]
	v_mfma_f32_16x16x32_bf16 v[32:35], v[158:161], v[174:177], v[32:35]
	v_mfma_f32_16x16x32_bf16 v[20:23], v[150:153], v[182:185], v[20:23]
	v_mfma_f32_16x16x32_bf16 v[16:19], v[158:161], v[182:185], v[16:19]
	v_mfma_f32_16x16x32_bf16 v[4:7], v[150:153], v[190:193], v[4:7]
	v_mfma_f32_16x16x32_bf16 v[0:3], v[158:161], v[190:193], v[0:3]
	s_add_u32 s10, s10, 0x100
	s_addc_u32 s11, s11, 0
	s_add_u32 s14, s14, 0x100
	s_addc_u32 s15, s15, 0
	s_cmp_ge_u32 s48, s72
	s_mov_b32 s12, s48
	s_setprio 0
	s_barrier
	s_cbranch_scc0 .LBB0_201
	s_and_b64 vcc, exec, s[34:35]
	s_cbranch_vccz .LBB0_204
	s_barrier

.LBB0_323:
	ds_read_b128 v[130:133], v241
	ds_read_b128 v[134:137], v241 offset:1024
	ds_read_b128 v[138:141], v241 offset:2048
	ds_read_b128 v[142:145], v241 offset:3072
	ds_read_b128 v[156:159], v241 offset:16384
	ds_read_b128 v[160:163], v241 offset:17408
	ds_read_b128 v[164:167], v241 offset:18432
	ds_read_b128 v[168:171], v241 offset:19456
	s_add_u32 s28, s10, 0xfff80080
	s_addc_u32 s29, s11, -1
	s_cmp_eq_u32 s74, 28
	s_cselect_b32 s31, s1, s29
	s_cselect_b32 s30, s34, s28
	s_cselect_b32 s29, s21, s73
	s_cselect_b32 s28, s35, s72
	s_add_i32 m0, s36, 0xc000
	ds_read_b128 v[172:175], v179
	ds_read_b128 v[202:205], v179 offset:1024
	ds_read_b128 v[206:209], v179 offset:2048
	ds_read_b128 v[210:213], v179 offset:3072
	ds_read_b128 v[214:217], v179 offset:4096
	ds_read_b128 v[218:221], v179 offset:5120
	ds_read_b128 v[222:225], v179 offset:6144
	ds_read_b128 v[242:245], v179 offset:7168
	global_load_lds_dwordx4 v152, s[10:11]
	s_add_i32 m0, s36, 0xe000
	s_nop 0
	global_load_lds_dwordx4 v154, s[10:11]
	s_waitcnt vmcnt(8)
	s_waitcnt lgkmcnt(0)
	s_barrier
	s_setprio 1
	v_mfma_f32_16x16x32_bf16 v[126:129], v[130:133], v[172:175], v[126:129]
	v_mfma_f32_16x16x32_bf16 v[122:125], v[138:141], v[172:175], v[122:125]
	v_mfma_f32_16x16x32_bf16 v[110:113], v[130:133], v[206:209], v[110:113]
	v_mfma_f32_16x16x32_bf16 v[106:109], v[138:141], v[206:209], v[106:109]
	v_mfma_f32_16x16x32_bf16 v[94:97], v[130:133], v[214:217], v[94:97]
	v_mfma_f32_16x16x32_bf16 v[90:93], v[138:141], v[214:217], v[90:93]
	v_mfma_f32_16x16x32_bf16 v[78:81], v[130:133], v[222:225], v[78:81]
	v_mfma_f32_16x16x32_bf16 v[74:77], v[138:141], v[222:225], v[74:77]
	v_mfma_f32_16x16x32_bf16 v[126:129], v[134:137], v[202:205], v[126:129]
	v_mfma_f32_16x16x32_bf16 v[122:125], v[142:145], v[202:205], v[122:125]
	v_mfma_f32_16x16x32_bf16 v[110:113], v[134:137], v[210:213], v[110:113]
	v_mfma_f32_16x16x32_bf16 v[106:109], v[142:145], v[210:213], v[106:109]
	v_mfma_f32_16x16x32_bf16 v[94:97], v[134:137], v[218:221], v[94:97]
	v_mfma_f32_16x16x32_bf16 v[90:93], v[142:145], v[218:221], v[90:93]
	v_mfma_f32_16x16x32_bf16 v[78:81], v[134:137], v[242:245], v[78:81]
	v_mfma_f32_16x16x32_bf16 v[74:77], v[142:145], v[242:245], v[74:77]
	s_setprio 0
	s_setprio 1
	v_mfma_f32_16x16x32_bf16 v[118:121], v[156:159], v[172:175], v[118:121]
	v_mfma_f32_16x16x32_bf16 v[114:117], v[164:167], v[172:175], v[114:117]
	v_mfma_f32_16x16x32_bf16 v[102:105], v[156:159], v[206:209], v[102:105]
	v_mfma_f32_16x16x32_bf16 v[98:101], v[164:167], v[206:209], v[98:101]
	v_mfma_f32_16x16x32_bf16 v[86:89], v[156:159], v[214:217], v[86:89]
	v_mfma_f32_16x16x32_bf16 v[82:85], v[164:167], v[214:217], v[82:85]
	v_mfma_f32_16x16x32_bf16 v[70:73], v[156:159], v[222:225], v[70:73]
	v_mfma_f32_16x16x32_bf16 v[66:69], v[164:167], v[222:225], v[66:69]
	v_mfma_f32_16x16x32_bf16 v[118:121], v[160:163], v[202:205], v[118:121]
	v_mfma_f32_16x16x32_bf16 v[114:117], v[168:171], v[202:205], v[114:117]
	v_mfma_f32_16x16x32_bf16 v[102:105], v[160:163], v[210:213], v[102:105]
	v_mfma_f32_16x16x32_bf16 v[98:101], v[168:171], v[210:213], v[98:101]
	v_mfma_f32_16x16x32_bf16 v[86:89], v[160:163], v[218:221], v[86:89]
	v_mfma_f32_16x16x32_bf16 v[82:85], v[168:171], v[218:221], v[82:85]
	v_mfma_f32_16x16x32_bf16 v[70:73], v[160:163], v[242:245], v[70:73]
	v_mfma_f32_16x16x32_bf16 v[66:69], v[168:171], v[242:245], v[66:69]
	s_setprio 0
	s_barrier
	s_mov_b32 m0, s37
	s_add_u32 s76, s28, 0x80000
	s_addc_u32 s77, s29, 0
	ds_read_b128 v[172:175], v179 offset:16384
	ds_read_b128 v[202:205], v179 offset:17408
	ds_read_b128 v[206:209], v179 offset:18432
	ds_read_b128 v[210:213], v179 offset:19456
	ds_read_b128 v[214:217], v179 offset:20480
	ds_read_b128 v[218:221], v179 offset:21504
	ds_read_b128 v[222:225], v179 offset:22528
	ds_read_b128 v[242:245], v179 offset:23552
	global_load_lds_dwordx4 v64, s[28:29]
	s_mov_b32 m0, s38
	s_nop 0
	global_load_lds_dwordx4 v146, s[28:29]
	s_mov_b32 m0, s39
	s_nop 0
	global_load_lds_dwordx4 v64, s[76:77]
	s_mov_b32 m0, s40
	s_nop 0
	global_load_lds_dwordx4 v146, s[76:77]
	s_mov_b32 m0, s36
	s_nop 0
	global_load_lds_dwordx4 v150, s[30:31]
	s_mov_b32 m0, s41
	s_nop 0
	global_load_lds_dwordx4 v148, s[30:31]
	s_waitcnt vmcnt(8)
	s_waitcnt lgkmcnt(0)
	s_barrier
	s_setprio 1
	v_mfma_f32_16x16x32_bf16 v[60:63], v[130:133], v[172:175], v[60:63]
	v_mfma_f32_16x16x32_bf16 v[56:59], v[138:141], v[172:175], v[56:59]
	v_mfma_f32_16x16x32_bf16 v[44:47], v[130:133], v[206:209], v[44:47]
	v_mfma_f32_16x16x32_bf16 v[40:43], v[138:141], v[206:209], v[40:43]
	v_mfma_f32_16x16x32_bf16 v[28:31], v[130:133], v[214:217], v[28:31]
	v_mfma_f32_16x16x32_bf16 v[24:27], v[138:141], v[214:217], v[24:27]
	v_mfma_f32_16x16x32_bf16 v[12:15], v[130:133], v[222:225], v[12:15]
	v_mfma_f32_16x16x32_bf16 v[8:11], v[138:141], v[222:225], v[8:11]
	v_mfma_f32_16x16x32_bf16 v[60:63], v[134:137], v[202:205], v[60:63]
	v_mfma_f32_16x16x32_bf16 v[56:59], v[142:145], v[202:205], v[56:59]
	v_mfma_f32_16x16x32_bf16 v[44:47], v[134:137], v[210:213], v[44:47]
	v_mfma_f32_16x16x32_bf16 v[40:43], v[142:145], v[210:213], v[40:43]
	v_mfma_f32_16x16x32_bf16 v[28:31], v[134:137], v[218:221], v[28:31]
	v_mfma_f32_16x16x32_bf16 v[24:27], v[142:145], v[218:221], v[24:27]
	v_mfma_f32_16x16x32_bf16 v[12:15], v[134:137], v[242:245], v[12:15]
	v_mfma_f32_16x16x32_bf16 v[8:11], v[142:145], v[242:245], v[8:11]
	s_setprio 0
	s_setprio 1
	v_mfma_f32_16x16x32_bf16 v[52:55], v[156:159], v[172:175], v[52:55]
	v_mfma_f32_16x16x32_bf16 v[48:51], v[164:167], v[172:175], v[48:51]
	v_mfma_f32_16x16x32_bf16 v[36:39], v[156:159], v[206:209], v[36:39]
	v_mfma_f32_16x16x32_bf16 v[32:35], v[164:167], v[206:209], v[32:35]
	v_mfma_f32_16x16x32_bf16 v[20:23], v[156:159], v[214:217], v[20:23]
	v_mfma_f32_16x16x32_bf16 v[16:19], v[164:167], v[214:217], v[16:19]
	v_mfma_f32_16x16x32_bf16 v[4:7], v[156:159], v[222:225], v[4:7]
	v_mfma_f32_16x16x32_bf16 v[0:3], v[164:167], v[222:225], v[0:3]
	v_mfma_f32_16x16x32_bf16 v[52:55], v[160:163], v[202:205], v[52:55]
	v_mfma_f32_16x16x32_bf16 v[48:51], v[168:171], v[202:205], v[48:51]
	v_mfma_f32_16x16x32_bf16 v[36:39], v[160:163], v[210:213], v[36:39]
	v_mfma_f32_16x16x32_bf16 v[32:35], v[168:171], v[210:213], v[32:35]
	v_mfma_f32_16x16x32_bf16 v[20:23], v[160:163], v[218:221], v[20:23]
	v_mfma_f32_16x16x32_bf16 v[16:19], v[168:171], v[218:221], v[16:19]
	v_mfma_f32_16x16x32_bf16 v[4:7], v[160:163], v[242:245], v[4:7]
	v_mfma_f32_16x16x32_bf16 v[0:3], v[168:171], v[242:245], v[0:3]
	s_setprio 0
	s_barrier
	ds_read_b128 v[130:133], v241 offset:32768
	ds_read_b128 v[134:137], v241 offset:33792
	ds_read_b128 v[138:141], v241 offset:34816
	ds_read_b128 v[142:145], v241 offset:35840
	ds_read_b128 v[156:159], v241 offset:49152
	ds_read_b128 v[160:163], v241 offset:50176
	ds_read_b128 v[164:167], v241 offset:51200
	ds_read_b128 v[168:171], v241 offset:52224
	s_add_u32 s56, s30, 0x80000
	s_addc_u32 s57, s31, 0
	s_mov_b32 m0, s42
	ds_read_b128 v[172:175], v179 offset:32768
	ds_read_b128 v[202:205], v179 offset:33792
	ds_read_b128 v[206:209], v179 offset:34816
	ds_read_b128 v[210:213], v179 offset:35840
	ds_read_b128 v[214:217], v179 offset:36864
	ds_read_b128 v[218:221], v179 offset:37888
	ds_read_b128 v[222:225], v179 offset:38912
	ds_read_b128 v[242:245], v179 offset:39936
	global_load_lds_dwordx4 v150, s[56:57]
	s_mov_b32 m0, s43
	s_nop 0
	global_load_lds_dwordx4 v148, s[56:57]
	s_waitcnt vmcnt(8)
	s_waitcnt lgkmcnt(0)
	s_barrier
	s_setprio 1
	v_mfma_f32_16x16x32_bf16 v[126:129], v[130:133], v[172:175], v[126:129]
	v_mfma_f32_16x16x32_bf16 v[122:125], v[138:141], v[172:175], v[122:125]
	v_mfma_f32_16x16x32_bf16 v[110:113], v[130:133], v[206:209], v[110:113]
	v_mfma_f32_16x16x32_bf16 v[106:109], v[138:141], v[206:209], v[106:109]
	v_mfma_f32_16x16x32_bf16 v[94:97], v[130:133], v[214:217], v[94:97]
	v_mfma_f32_16x16x32_bf16 v[90:93], v[138:141], v[214:217], v[90:93]
	v_mfma_f32_16x16x32_bf16 v[78:81], v[130:133], v[222:225], v[78:81]
	v_mfma_f32_16x16x32_bf16 v[74:77], v[138:141], v[222:225], v[74:77]
	v_mfma_f32_16x16x32_bf16 v[126:129], v[134:137], v[202:205], v[126:129]
	v_mfma_f32_16x16x32_bf16 v[122:125], v[142:145], v[202:205], v[122:125]
	v_mfma_f32_16x16x32_bf16 v[110:113], v[134:137], v[210:213], v[110:113]
	v_mfma_f32_16x16x32_bf16 v[106:109], v[142:145], v[210:213], v[106:109]
	v_mfma_f32_16x16x32_bf16 v[94:97], v[134:137], v[218:221], v[94:97]
	v_mfma_f32_16x16x32_bf16 v[90:93], v[142:145], v[218:221], v[90:93]
	v_mfma_f32_16x16x32_bf16 v[78:81], v[134:137], v[242:245], v[78:81]
	v_mfma_f32_16x16x32_bf16 v[74:77], v[142:145], v[242:245], v[74:77]
	s_setprio 0
	s_setprio 1
	v_mfma_f32_16x16x32_bf16 v[118:121], v[156:159], v[172:175], v[118:121]
	v_mfma_f32_16x16x32_bf16 v[114:117], v[164:167], v[172:175], v[114:117]
	v_mfma_f32_16x16x32_bf16 v[102:105], v[156:159], v[206:209], v[102:105]
	v_mfma_f32_16x16x32_bf16 v[98:101], v[164:167], v[206:209], v[98:101]
	v_mfma_f32_16x16x32_bf16 v[86:89], v[156:159], v[214:217], v[86:89]
	v_mfma_f32_16x16x32_bf16 v[82:85], v[164:167], v[214:217], v[82:85]
	v_mfma_f32_16x16x32_bf16 v[70:73], v[156:159], v[222:225], v[70:73]
	v_mfma_f32_16x16x32_bf16 v[66:69], v[164:167], v[222:225], v[66:69]
	v_mfma_f32_16x16x32_bf16 v[118:121], v[160:163], v[202:205], v[118:121]
	v_mfma_f32_16x16x32_bf16 v[114:117], v[168:171], v[202:205], v[114:117]
	v_mfma_f32_16x16x32_bf16 v[102:105], v[160:163], v[210:213], v[102:105]
	v_mfma_f32_16x16x32_bf16 v[98:101], v[168:171], v[210:213], v[98:101]
	v_mfma_f32_16x16x32_bf16 v[86:89], v[160:163], v[218:221], v[86:89]
	v_mfma_f32_16x16x32_bf16 v[82:85], v[168:171], v[218:221], v[82:85]
	v_mfma_f32_16x16x32_bf16 v[70:73], v[160:163], v[242:245], v[70:73]
	v_mfma_f32_16x16x32_bf16 v[66:69], v[168:171], v[242:245], v[66:69]
	s_setprio 0
	s_barrier
	s_add_i32 m0, s46, 0xffffff80
	s_add_u32 s58, s28, 0x80080
	s_addc_u32 s59, s29, 0
	ds_read_b128 v[172:175], v179 offset:49152
	ds_read_b128 v[202:205], v179 offset:50176
	ds_read_b128 v[206:209], v179 offset:51200
	ds_read_b128 v[210:213], v179 offset:52224
	ds_read_b128 v[214:217], v179 offset:53248
	ds_read_b128 v[218:221], v179 offset:54272
	ds_read_b128 v[222:225], v179 offset:55296
	ds_read_b128 v[242:245], v179 offset:56320
	global_load_lds_dwordx4 v64, s[28:29] offset:128
	s_add_i32 m0, s47, 0xffffff80
	s_nop 0
	global_load_lds_dwordx4 v146, s[28:29] offset:128
	s_mov_b32 m0, s50
	s_nop 0
	global_load_lds_dwordx4 v64, s[58:59]
	s_mov_b32 m0, s51
	s_nop 0
	global_load_lds_dwordx4 v146, s[58:59]
	s_add_i32 m0, s48, 0xffffff80
	s_nop 0
	global_load_lds_dwordx4 v150, s[30:31] offset:128
	s_add_i32 m0, s49, 0xffffff80
	s_nop 0
	global_load_lds_dwordx4 v148, s[30:31] offset:128
	s_waitcnt vmcnt(8)
	s_waitcnt lgkmcnt(0)
	s_barrier
	s_setprio 1
	v_mfma_f32_16x16x32_bf16 v[60:63], v[130:133], v[172:175], v[60:63]
	v_mfma_f32_16x16x32_bf16 v[56:59], v[138:141], v[172:175], v[56:59]
	v_mfma_f32_16x16x32_bf16 v[44:47], v[130:133], v[206:209], v[44:47]
	v_mfma_f32_16x16x32_bf16 v[40:43], v[138:141], v[206:209], v[40:43]
	v_mfma_f32_16x16x32_bf16 v[28:31], v[130:133], v[214:217], v[28:31]
	v_mfma_f32_16x16x32_bf16 v[24:27], v[138:141], v[214:217], v[24:27]
	v_mfma_f32_16x16x32_bf16 v[12:15], v[130:133], v[222:225], v[12:15]
	v_mfma_f32_16x16x32_bf16 v[8:11], v[138:141], v[222:225], v[8:11]
	v_mfma_f32_16x16x32_bf16 v[60:63], v[134:137], v[202:205], v[60:63]
	v_mfma_f32_16x16x32_bf16 v[56:59], v[142:145], v[202:205], v[56:59]
	v_mfma_f32_16x16x32_bf16 v[44:47], v[134:137], v[210:213], v[44:47]
	v_mfma_f32_16x16x32_bf16 v[40:43], v[142:145], v[210:213], v[40:43]
	v_mfma_f32_16x16x32_bf16 v[28:31], v[134:137], v[218:221], v[28:31]
	v_mfma_f32_16x16x32_bf16 v[24:27], v[142:145], v[218:221], v[24:27]
	v_mfma_f32_16x16x32_bf16 v[12:15], v[134:137], v[242:245], v[12:15]
	v_mfma_f32_16x16x32_bf16 v[8:11], v[142:145], v[242:245], v[8:11]
	s_setprio 0
	s_setprio 1
	v_mfma_f32_16x16x32_bf16 v[52:55], v[156:159], v[172:175], v[52:55]
	v_mfma_f32_16x16x32_bf16 v[48:51], v[164:167], v[172:175], v[48:51]
	v_mfma_f32_16x16x32_bf16 v[36:39], v[156:159], v[206:209], v[36:39]
	v_mfma_f32_16x16x32_bf16 v[32:35], v[164:167], v[206:209], v[32:35]
	v_mfma_f32_16x16x32_bf16 v[20:23], v[156:159], v[214:217], v[20:23]
	v_mfma_f32_16x16x32_bf16 v[16:19], v[164:167], v[214:217], v[16:19]
	v_mfma_f32_16x16x32_bf16 v[4:7], v[156:159], v[222:225], v[4:7]
	v_mfma_f32_16x16x32_bf16 v[0:3], v[164:167], v[222:225], v[0:3]
	v_mfma_f32_16x16x32_bf16 v[52:55], v[160:163], v[202:205], v[52:55]
	v_mfma_f32_16x16x32_bf16 v[48:51], v[168:171], v[202:205], v[48:51]
	v_mfma_f32_16x16x32_bf16 v[36:39], v[160:163], v[210:213], v[36:39]
	v_mfma_f32_16x16x32_bf16 v[32:35], v[168:171], v[210:213], v[32:35]
	v_mfma_f32_16x16x32_bf16 v[20:23], v[160:163], v[218:221], v[20:23]
	v_mfma_f32_16x16x32_bf16 v[16:19], v[168:171], v[218:221], v[16:19]
	v_mfma_f32_16x16x32_bf16 v[4:7], v[160:163], v[242:245], v[4:7]
	v_mfma_f32_16x16x32_bf16 v[0:3], v[168:171], v[242:245], v[0:3]
	s_add_i32 s74, s74, 2
	s_add_u32 s10, s10, 0x100
	s_addc_u32 s11, s11, 0
	s_add_u32 s72, s72, 0x100
	s_addc_u32 s73, s73, 0
	s_cmp_gt_u32 s74, 29
	s_setprio 0
	s_barrier
	s_cbranch_scc0 .LBB0_323
	s_and_b64 vcc, exec, s[16:17]
	s_cbranch_vccz .LBB0_326
	s_barrier

.LBB0_465:
	s_and_b64 vcc, exec, s[0:1]
	s_mov_b32 s36, 0x10000
	s_mov_b32 s37, 0x14000
	s_movk_i32 s38, 0x4000
	s_mov_b32 s39, 0x18000
	s_mov_b32 s40, 0x8000
	s_mov_b32 s41, 0x1c000
	s_mov_b32 s42, 0xc000
	s_mov_b32 s43, 0x30000
	s_mov_b32 s44, 0x60000
	s_mov_b32 s45, 0x210000
	s_mov_b32 s46, 0x20000
	s_mov_b32 s47, 0x24000
	s_mov_b32 s48, 0x28000
	s_mov_b32 s49, 0x2c000
	s_mov_b32 s50, 0x34000
	s_mov_b32 s51, 0x38000
	s_mov_b32 s52, 0x3c000
	s_mov_b32 s53, 0x40000
	s_mov_b32 s54, 0x44000
	s_mov_b32 s55, 0x48000
	s_mov_b32 s62, 0x4c000
	s_mov_b32 s63, 0x50000
	s_mov_b32 s64, 0x54000
	s_mov_b32 s65, 0x58000
	s_cbranch_vccz .LBB0_636
	v_readlane_b32 s0, v254, 53
	v_readlane_b32 s1, v254, 12
	s_lshl_b32 s0, s0, 3
	s_add_i32 s8, s86, s1
	s_cmp_eq_u32 s101, 0x103ff
	s_cselect_b32 s1, 0x8200, 0
	s_add_i32 s8, s8, s1
	s_cmp_gt_i32 s8, s101
	s_cbranch_scc1 .LBB0_615
	v_lshlrev_b32_e32 v0, 3, v240
	v_lshrrev_b32_e32 v72, 3, v240
	v_and_b32_e32 v70, 56, v0
	s_lshl_b32 s5, s86, 14
	v_lshrrev_b32_e32 v66, 5, v240
	v_mul_u32_u24_e32 v0, 0x84, v70
	s_waitcnt lgkmcnt(0)
	v_lshlrev_b32_e32 v1, 2, v72
	s_movk_i32 s6, 0x84
	v_or3_b32 v73, s5, v0, v1
	v_or_b32_e32 v0, 2, v66
	v_mov_b32_e32 v1, 0x108
	s_add_u32 s1, s94, 0xdc00000
	v_mad_u32_u24 v78, v0, s6, v1
	v_mov_b32_e32 v1, 0x210
	s_addc_u32 s2, s95, 0
	v_and_b32_e32 v68, 31, v194
	v_mad_u32_u24 v79, v0, s6, v1
	v_mov_b32_e32 v1, 0x318
	v_lshl_or_b32 v69, v68, 2, s5
	s_add_u32 s5, s94, 0x8400000
	v_mad_u32_u24 v80, v0, s6, v1
	v_mov_b32_e32 v1, 0x420
	s_addc_u32 s9, s95, 0
	v_mad_u32_u24 v81, v0, s6, v1
	v_mov_b32_e32 v1, 0x528
	v_mad_u32_u24 v82, v0, s6, v1
	v_mov_b32_e32 v1, 0x630
	s_add_u32 s22, s94, 0x7400000
	v_mad_u32_u24 v83, v0, s6, v1
	v_mov_b32_e32 v1, 0x738
	s_addc_u32 s23, s95, 0
	v_mad_u32_u24 v84, v0, s6, v1
	v_mov_b32_e32 v1, 0x840
	s_add_u32 s24, s94, 0x6400000
	v_mad_u32_u24 v85, v0, s6, v1
	v_mov_b32_e32 v1, 0x948
	s_addc_u32 s25, s95, 0
	v_mad_u32_u24 v86, v0, s6, v1
	v_mov_b32_e32 v1, 0xa50
	s_add_u32 s26, s94, 0x400000
	v_mad_u32_u24 v87, v0, s6, v1
	v_mov_b32_e32 v1, 0xb58
	s_addc_u32 s27, s95, 0
	v_mad_u32_u24 v88, v0, s6, v1
	v_mov_b32_e32 v1, 0xc60
	s_cmp_lg_u64 s[70:71], 0
	v_mad_u32_u24 v89, v0, s6, v1
	v_mov_b32_e32 v1, 0xd68
	s_cselect_b64 s[10:11], -1, 0
	s_cmp_lg_u64 s[58:59], 0
	v_mad_u32_u24 v71, v66, s6, v69
	v_or_b32_e32 v74, 8, v72
	v_or_b32_e32 v75, 16, v72
	v_or_b32_e32 v76, 24, v72
	v_mul_u32_u24_e32 v77, 0x84, v0
	v_mad_u32_u24 v90, v0, s6, v1
	s_cselect_b64 s[12:13], -1, 0
	v_mov_b32_e32 v67, v65
	s_lshl_b32 s28, s8, 5
	s_lshl_b32 s29, s0, 5
	s_mov_b32 s30, s8
	s_branch .LBB0_471

.LBB0_470:
	s_add_i32 s30, s30, s0
	s_add_i32 s28, s28, s29
	s_cmp_gt_i32 s30, s101
	s_cbranch_scc1 .LBB0_615

.LBB0_615:
	s_cmp_eq_u32 s101, 0x103ff
	s_cbranch_scc1 .Lpp_done
	s_cmpk_gt_i32 s8, 0x3fff
	s_cbranch_scc1 .LBB0_620
	v_and_b32_e32 v0, 64, v233
	v_add_u32_e32 v0, 64, v0
	s_waitcnt lgkmcnt(0)
	v_xor_b32_e32 v1, 1, v233
	v_cmp_lt_i32_e32 vcc, v1, v0
	s_ashr_i32 s9, s8, 31
	s_lshl_b64 s[10:11], s[8:9], 2
	v_cndmask_b32_e32 v1, v233, v1, vcc
	v_lshlrev_b32_e32 v6, 2, v1
	v_xor_b32_e32 v1, 2, v233
	v_cmp_lt_i32_e32 vcc, v1, v0
	s_add_u32 s2, s10, 0x10000
	s_addc_u32 s5, s11, 0
	v_cndmask_b32_e32 v1, v233, v1, vcc
	v_lshlrev_b32_e32 v7, 2, v1
	v_xor_b32_e32 v1, 4, v233
	v_cmp_lt_i32_e32 vcc, v1, v0
	s_ashr_i32 s1, s0, 31
	s_lshl_b64 s[10:11], s[0:1], 2
	v_cndmask_b32_e32 v1, v233, v1, vcc
	v_lshlrev_b32_e32 v8, 2, v1
	v_xor_b32_e32 v1, 8, v233
	v_cmp_lt_i32_e32 vcc, v1, v0
	s_lshl_b64 s[12:13], s[8:9], 13
	s_add_u32 s12, s56, s12
	v_cndmask_b32_e32 v1, v233, v1, vcc
	v_lshlrev_b32_e32 v9, 2, v1
	v_xor_b32_e32 v1, 16, v233
	v_cmp_lt_i32_e32 vcc, v1, v0
	v_lshlrev_b32_e32 v64, 4, v240
	s_addc_u32 s13, s57, s13
	v_cndmask_b32_e32 v1, v233, v1, vcc
	v_lshlrev_b32_e32 v10, 2, v1
	v_xor_b32_e32 v1, 32, v233
	v_cmp_lt_i32_e32 vcc, v1, v0
	s_lshl_b64 s[14:15], s[8:9], 12
	v_cmp_eq_u32_e64 s[6:7], 0, v240
	v_cndmask_b32_e32 v0, v233, v1, vcc
	v_lshlrev_b32_e32 v11, 2, v0
	v_lshl_add_u64 v[0:1], s[12:13], 0, v[64:65]
	s_mov_b64 s[12:13], 0x1000
	v_lshl_add_u64 v[0:1], v[0:1], 0, s[12:13]
	s_lshl_b64 s[12:13], s[0:1], 13
	v_lshl_or_b32 v2, v240, 3, s14
	v_mov_b32_e32 v3, s15
	s_lshl_b64 s[14:15], s[0:1], 12
	s_branch .LBB0_618
